# v33 + FoX: s_setprio 1 in QK-scores segment, 0 in softmax+PV
# baseline (speedup 1.0000x reference)
.LBB0_720:
	s_add_i32 s11, s0, 0
	s_lshl_b32 s0, s1, 1
	s_and_b32 s0, s0, -4
	s_add_i32 s96, s0, 0
	s_add_i32 s96, s96, 0x1b000
	s_cmp_le_u32 s5, s33
	v_lshl_add_u32 v141, v130, 2, s11
	s_cselect_b64 s[0:1], -1, 0
	s_cmp_gt_u32 s5, s33
	v_add_u32_e32 v140, s11, v107
	v_add_u32_e32 v139, s11, v124
	v_add_u32_e32 v138, s11, v125
	v_add_u32_e32 v0, s11, v126
	s_cbranch_scc1 .LBB0_723
	s_setprio 1
	v_mov_b32_e32 v50, s96
	ds_read_b32 v58, v50
	v_sub_f32_e32 v59, v113, v137
	ds_read_b128 v[74:77], v141 offset:32832
	ds_read_b128 v[50:53], v141 offset:32768
	ds_read_b128 v[54:57], v141 offset:32800
	s_waitcnt lgkmcnt(0)
	v_sub_f32_e32 v158, v59, v58
	ds_read_b128 v[58:61], v141 offset:32864
	ds_read_b128 v[146:149], v139
	v_sub_f32_e32 v53, v158, v53
	v_sub_f32_e32 v57, v158, v57
	v_sub_f32_e32 v56, v158, v56
	s_waitcnt lgkmcnt(0)
	v_sub_f32_e32 v65, v158, v61
	v_sub_f32_e32 v64, v158, v60
	v_sub_f32_e32 v63, v158, v59
	v_sub_f32_e32 v62, v158, v58
	v_sub_f32_e32 v61, v158, v77
	v_sub_f32_e32 v60, v158, v76
	v_sub_f32_e32 v59, v158, v75
	v_sub_f32_e32 v58, v158, v74
	ds_read_b128 v[74:77], v140
	v_sub_f32_e32 v55, v158, v55
	v_sub_f32_e32 v54, v158, v54
	v_sub_f32_e32 v52, v158, v52
	v_sub_f32_e32 v51, v158, v51
	v_sub_f32_e32 v50, v158, v50
	ds_read_b128 v[66:69], v141 offset:32896
	ds_read_b128 v[70:73], v141 offset:32928
	ds_read_b128 v[142:145], v141 offset:32960
	ds_read_b128 v[78:81], v141 offset:32992
	ds_read_b128 v[150:153], v138
	s_waitcnt lgkmcnt(0)
	v_mfma_f32_32x32x16_bf16 v[50:65], v[74:77], v[86:89], v[50:65]
	ds_read_b128 v[154:157], v0
	v_sub_f32_e32 v77, v158, v145
	v_sub_f32_e32 v76, v158, v144
	v_sub_f32_e32 v75, v158, v143
	v_sub_f32_e32 v74, v158, v142
	v_sub_f32_e32 v81, v158, v81
	v_sub_f32_e32 v80, v158, v80
	v_mfma_f32_32x32x16_bf16 v[50:65], v[146:149], v[90:93], v[50:65]
	ds_read_b128 v[142:145], v140 offset:4096
	v_sub_f32_e32 v79, v158, v79
	v_sub_f32_e32 v78, v158, v78
	v_sub_f32_e32 v73, v158, v73
	v_sub_f32_e32 v72, v158, v72
	v_sub_f32_e32 v71, v158, v71
	v_sub_f32_e32 v70, v158, v70
	v_mfma_f32_32x32x16_bf16 v[50:65], v[150:153], v[94:97], v[50:65]
	v_sub_f32_e32 v69, v158, v69
	v_sub_f32_e32 v68, v158, v68
	v_sub_f32_e32 v67, v158, v67
	v_sub_f32_e32 v66, v158, v66
	ds_read_b128 v[146:149], v139 offset:4096
	s_cmp_lg_u32 s92, s5
	s_waitcnt lgkmcnt(0)
	v_mfma_f32_32x32x16_bf16 v[66:81], v[142:145], v[86:89], v[66:81]
	ds_read_b128 v[142:145], v138 offset:4096
	v_mfma_f32_32x32x16_bf16 v[66:81], v[146:149], v[90:93], v[66:81]
	s_waitcnt lgkmcnt(0)
	v_mfma_f32_32x32x16_bf16 v[66:81], v[142:145], v[94:97], v[66:81]
	ds_read_b128 v[142:145], v0 offset:4096
	s_waitcnt lgkmcnt(0)
	v_mfma_f32_32x32x16_bf16 v[66:81], v[142:145], v[98:101], v[66:81]
	v_mfma_f32_32x32x16_bf16 v[50:65], v[154:157], v[98:101], v[50:65]
	s_cbranch_scc1 .LBB0_723
	s_nop 10
	v_cndmask_b32_e64 v142, v50, v136, s[14:15]
	v_cndmask_b32_e64 v66, v66, v136, s[16:17]
	v_cndmask_b32_e64 v50, v142, v50, s[18:19]
	v_cndmask_b32_e64 v51, v136, v51, s[18:19]
	v_cndmask_b32_e64 v67, v67, v136, s[20:21]
	v_cndmask_b32_e64 v52, v52, v136, s[22:23]
	v_cndmask_b32_e64 v68, v68, v136, s[24:25]
	v_cndmask_b32_e64 v53, v53, v136, s[26:27]
	v_cndmask_b32_e64 v69, v69, v136, s[28:29]
	v_cndmask_b32_e64 v54, v54, v136, s[30:31]
	v_cndmask_b32_e64 v70, v70, v136, s[34:35]
	v_cndmask_b32_e64 v55, v55, v136, s[36:37]
	v_cndmask_b32_e64 v71, v71, v136, s[38:39]
	v_cndmask_b32_e64 v56, v56, v136, s[40:41]
	v_cndmask_b32_e64 v72, v72, v136, s[42:43]
	v_cndmask_b32_e64 v57, v57, v136, s[44:45]
	v_cndmask_b32_e64 v73, v73, v136, s[46:47]
	v_cndmask_b32_e64 v58, v58, v136, s[48:49]
	v_cndmask_b32_e64 v74, v74, v136, s[50:51]
	v_cndmask_b32_e64 v59, v59, v136, s[52:53]
	v_cndmask_b32_e64 v75, v75, v136, s[54:55]
	v_cndmask_b32_e64 v60, v60, v136, s[56:57]
	v_cndmask_b32_e64 v76, v76, v136, s[58:59]
	v_cndmask_b32_e64 v61, v61, v136, s[60:61]
	v_cndmask_b32_e64 v77, v77, v136, s[62:63]
	v_cndmask_b32_e64 v62, v62, v136, s[64:65]
	v_cndmask_b32_e64 v78, v78, v136, s[66:67]
	v_cndmask_b32_e64 v63, v63, v136, s[68:69]
	v_cndmask_b32_e64 v79, v79, v136, s[70:71]
	v_cndmask_b32_e64 v64, v64, v136, s[72:73]
	v_cndmask_b32_e64 v80, v80, v136, s[74:75]
	v_cndmask_b32_e64 v65, v65, v136, s[76:77]
	v_cndmask_b32_e64 v81, v81, v136, s[78:79]
.LBB0_723:
	s_andn2_b64 vcc, exec, s[0:1]
	s_cbranch_vccnz .LBB0_729
	s_setprio 0
	s_nop 8
	v_max_f32_e32 v142, v50, v51
	v_max3_f32 v142, v142, v52, v53
	v_max3_f32 v142, v142, v54, v55
	v_max3_f32 v142, v142, v56, v57
	v_max3_f32 v142, v142, v58, v59
	v_max3_f32 v142, v142, v60, v61
	v_max3_f32 v142, v142, v62, v63
	v_max3_f32 v142, v142, v64, v65
	v_mov_b32_e32 v143, v142
	s_nop 1
	v_permlane32_swap_b32_e32 v142, v143
	v_max_f32_e32 v142, v142, v143
	s_cmp_eq_u32 s91, 0
	s_cselect_b64 s[0:1], -1, 0
	v_cmp_lt_f32_e32 vcc, s8, v142
	s_or_b64 vcc, s[0:1], vcc
	s_cbranch_vccz .LBB0_726
	v_max_f32_e32 v143, v142, v142
	v_max_f32_e32 v143, 0, v143
	v_cndmask_b32_e64 v142, v143, v142, s[0:1]
	v_exp_f32_e64 v143, -v142
	v_add_f32_e32 v137, v137, v142
	v_sub_f32_e32 v81, v81, v142
	v_sub_f32_e32 v80, v80, v142
	v_cndmask_b32_e64 v144, v143, 1.0, s[0:1]
	v_pk_add_f32 v[50:51], v[50:51], v[142:143] op_sel_hi:[1,0] neg_lo:[0,1] neg_hi:[0,1]
	v_pk_add_f32 v[52:53], v[52:53], v[142:143] op_sel_hi:[1,0] neg_lo:[0,1] neg_hi:[0,1]
	v_mul_f32_e32 v34, v34, v144
	v_pk_add_f32 v[54:55], v[54:55], v[142:143] op_sel_hi:[1,0] neg_lo:[0,1] neg_hi:[0,1]
	v_pk_add_f32 v[56:57], v[56:57], v[142:143] op_sel_hi:[1,0] neg_lo:[0,1] neg_hi:[0,1]
	v_pk_add_f32 v[58:59], v[58:59], v[142:143] op_sel_hi:[1,0] neg_lo:[0,1] neg_hi:[0,1]
	v_pk_add_f32 v[60:61], v[60:61], v[142:143] op_sel_hi:[1,0] neg_lo:[0,1] neg_hi:[0,1]
	v_pk_add_f32 v[62:63], v[62:63], v[142:143] op_sel_hi:[1,0] neg_lo:[0,1] neg_hi:[0,1]
	v_pk_add_f32 v[64:65], v[64:65], v[142:143] op_sel_hi:[1,0] neg_lo:[0,1] neg_hi:[0,1]
	v_sub_f32_e32 v79, v79, v142
	v_sub_f32_e32 v78, v78, v142
	v_sub_f32_e32 v77, v77, v142
	v_sub_f32_e32 v76, v76, v142
	v_sub_f32_e32 v75, v75, v142
	v_sub_f32_e32 v74, v74, v142
	v_sub_f32_e32 v73, v73, v142
	v_sub_f32_e32 v72, v72, v142
	v_sub_f32_e32 v71, v71, v142
	v_sub_f32_e32 v70, v70, v142
	v_sub_f32_e32 v69, v69, v142
	v_sub_f32_e32 v68, v68, v142
	v_sub_f32_e32 v67, v67, v142
	v_sub_f32_e32 v66, v66, v142
	v_pk_mul_f32 v[32:33], v[32:33], v[144:145] op_sel_hi:[1,0]
	v_pk_mul_f32 v[30:31], v[30:31], v[144:145] op_sel_hi:[1,0]
	v_pk_mul_f32 v[28:29], v[28:29], v[144:145] op_sel_hi:[1,0]
	v_pk_mul_f32 v[26:27], v[26:27], v[144:145] op_sel_hi:[1,0]
	v_pk_mul_f32 v[24:25], v[24:25], v[144:145] op_sel_hi:[1,0]
	v_pk_mul_f32 v[22:23], v[22:23], v[144:145] op_sel_hi:[1,0]
	v_pk_mul_f32 v[20:21], v[20:21], v[144:145] op_sel_hi:[1,0]
	v_pk_mul_f32 v[18:19], v[18:19], v[144:145] op_sel_hi:[1,0]
	v_pk_mul_f32 v[16:17], v[16:17], v[144:145] op_sel_hi:[1,0]
	v_pk_mul_f32 v[14:15], v[14:15], v[144:145] op_sel_hi:[1,0]
	v_pk_mul_f32 v[12:13], v[12:13], v[144:145] op_sel_hi:[1,0]
	v_pk_mul_f32 v[10:11], v[10:11], v[144:145] op_sel_hi:[1,0]
	v_pk_mul_f32 v[8:9], v[8:9], v[144:145] op_sel_hi:[1,0]
	v_pk_mul_f32 v[6:7], v[6:7], v[144:145] op_sel_hi:[1,0]
	v_pk_mul_f32 v[4:5], v[4:5], v[144:145] op_sel_hi:[1,0]
	v_pk_mul_f32 v[2:3], v[2:3], v[144:145] op_sel_hi:[1,0]

.LBB0_729:
	s_cmp_lt_u32 s5, s33
	s_cselect_b64 s[0:1], -1, 0
	s_cmp_ge_u32 s5, s33
	s_cbranch_scc1 .LBB0_732
	s_setprio 1
	s_nop 4
	v_mov_b32_e32 v50, s96
	ds_read_b32 v58, v50
	v_sub_f32_e32 v59, v113, v137
	ds_read_b128 v[74:77], v141 offset:33088
	ds_read_b128 v[50:53], v141 offset:33024
	ds_read_b128 v[54:57], v141 offset:33056
	s_waitcnt lgkmcnt(0)
	v_sub_f32_e32 v158, v59, v58
	ds_read_b128 v[58:61], v141 offset:33120
	ds_read_b128 v[146:149], v139 offset:8192
	v_sub_f32_e32 v53, v158, v53
	v_sub_f32_e32 v57, v158, v57
	v_sub_f32_e32 v56, v158, v56
	s_waitcnt lgkmcnt(0)
	v_sub_f32_e32 v65, v158, v61
	v_sub_f32_e32 v64, v158, v60
	v_sub_f32_e32 v63, v158, v59
	v_sub_f32_e32 v62, v158, v58
	v_sub_f32_e32 v61, v158, v77
	v_sub_f32_e32 v60, v158, v76
	v_sub_f32_e32 v59, v158, v75
	v_sub_f32_e32 v58, v158, v74
	ds_read_b128 v[74:77], v140 offset:8192
	v_sub_f32_e32 v55, v158, v55
	v_sub_f32_e32 v54, v158, v54
	v_sub_f32_e32 v52, v158, v52
	v_sub_f32_e32 v51, v158, v51
	v_sub_f32_e32 v50, v158, v50
	ds_read_b128 v[66:69], v141 offset:33152
	ds_read_b128 v[70:73], v141 offset:33184
	ds_read_b128 v[142:145], v141 offset:33216
	ds_read_b128 v[78:81], v141 offset:33248
	ds_read_b128 v[150:153], v138 offset:8192
	s_waitcnt lgkmcnt(0)
	v_mfma_f32_32x32x16_bf16 v[50:65], v[74:77], v[86:89], v[50:65]
	ds_read_b128 v[154:157], v0 offset:8192
	v_sub_f32_e32 v75, v158, v143
	v_sub_f32_e32 v74, v158, v142
	v_sub_f32_e32 v81, v158, v81
	v_sub_f32_e32 v80, v158, v80
	v_sub_f32_e32 v79, v158, v79
	v_sub_f32_e32 v78, v158, v78
	v_mfma_f32_32x32x16_bf16 v[50:65], v[146:149], v[90:93], v[50:65]
	ds_read_b128 v[140:143], v140 offset:12288
	v_sub_f32_e32 v77, v158, v145
	v_sub_f32_e32 v76, v158, v144
	v_sub_f32_e32 v73, v158, v73
	v_sub_f32_e32 v72, v158, v72
	v_sub_f32_e32 v71, v158, v71
	v_sub_f32_e32 v70, v158, v70
	v_mfma_f32_32x32x16_bf16 v[50:65], v[150:153], v[94:97], v[50:65]
	v_sub_f32_e32 v69, v158, v69
	v_sub_f32_e32 v68, v158, v68
	v_sub_f32_e32 v67, v158, v67
	v_sub_f32_e32 v66, v158, v66
	ds_read_b128 v[144:147], v139 offset:12288
	s_cmp_lg_u32 s4, s5
	s_waitcnt lgkmcnt(0)
	v_mfma_f32_32x32x16_bf16 v[66:81], v[140:143], v[86:89], v[66:81]
	ds_read_b128 v[138:141], v138 offset:12288
	v_mfma_f32_32x32x16_bf16 v[66:81], v[144:147], v[90:93], v[66:81]
	s_waitcnt lgkmcnt(0)
	v_mfma_f32_32x32x16_bf16 v[66:81], v[138:141], v[94:97], v[66:81]
	ds_read_b128 v[138:141], v0 offset:12288
	s_waitcnt lgkmcnt(0)
	v_mfma_f32_32x32x16_bf16 v[66:81], v[138:141], v[98:101], v[66:81]
	v_mfma_f32_32x32x16_bf16 v[50:65], v[154:157], v[98:101], v[50:65]
	s_cbranch_scc1 .LBB0_732
	s_nop 10
	v_cndmask_b32_e64 v0, v50, v136, s[14:15]
	v_cndmask_b32_e64 v66, v66, v136, s[16:17]
	v_cndmask_b32_e64 v50, v0, v50, s[18:19]
	v_cndmask_b32_e64 v51, v136, v51, s[18:19]
	v_cndmask_b32_e64 v67, v67, v136, s[20:21]
	v_cndmask_b32_e64 v52, v52, v136, s[22:23]
	v_cndmask_b32_e64 v68, v68, v136, s[24:25]
	v_cndmask_b32_e64 v53, v53, v136, s[26:27]
	v_cndmask_b32_e64 v69, v69, v136, s[28:29]
	v_cndmask_b32_e64 v54, v54, v136, s[30:31]
	v_cndmask_b32_e64 v70, v70, v136, s[34:35]
	v_cndmask_b32_e64 v55, v55, v136, s[36:37]
	v_cndmask_b32_e64 v71, v71, v136, s[38:39]
	v_cndmask_b32_e64 v56, v56, v136, s[40:41]
	v_cndmask_b32_e64 v72, v72, v136, s[42:43]
	v_cndmask_b32_e64 v57, v57, v136, s[44:45]
	v_cndmask_b32_e64 v73, v73, v136, s[46:47]
	v_cndmask_b32_e64 v58, v58, v136, s[48:49]
	v_cndmask_b32_e64 v74, v74, v136, s[50:51]
	v_cndmask_b32_e64 v59, v59, v136, s[52:53]
	v_cndmask_b32_e64 v75, v75, v136, s[54:55]
	v_cndmask_b32_e64 v60, v60, v136, s[56:57]
	v_cndmask_b32_e64 v76, v76, v136, s[58:59]
	v_cndmask_b32_e64 v61, v61, v136, s[60:61]
	v_cndmask_b32_e64 v77, v77, v136, s[62:63]
	v_cndmask_b32_e64 v62, v62, v136, s[64:65]
	v_cndmask_b32_e64 v78, v78, v136, s[66:67]
	v_cndmask_b32_e64 v63, v63, v136, s[68:69]
	v_cndmask_b32_e64 v79, v79, v136, s[70:71]
	v_cndmask_b32_e64 v64, v64, v136, s[72:73]
	v_cndmask_b32_e64 v80, v80, v136, s[74:75]
	v_cndmask_b32_e64 v65, v65, v136, s[76:77]
	v_cndmask_b32_e64 v81, v81, v136, s[78:79]
.LBB0_732:
	s_andn2_b64 vcc, exec, s[0:1]
	s_cbranch_vccnz .LBB0_738
	s_setprio 0
	s_nop 8
	v_max_f32_e32 v0, v50, v51
	v_max3_f32 v0, v0, v52, v53
	v_max3_f32 v0, v0, v54, v55
	v_max3_f32 v0, v0, v56, v57
	v_max3_f32 v0, v0, v58, v59
	v_max3_f32 v0, v0, v60, v61
	v_max3_f32 v0, v0, v62, v63
	v_max3_f32 v0, v0, v64, v65
	v_mov_b32_e32 v138, v0
	s_nop 1
	v_permlane32_swap_b32_e32 v0, v138
	v_max_f32_e32 v0, v0, v138
	v_cmp_lt_f32_e32 vcc, s8, v0
	s_cbranch_vccz .LBB0_735
	v_max_f32_e32 v0, v0, v0
	v_max_f32_e32 v0, 0, v0
	v_exp_f32_e64 v138, -v0
	v_add_f32_e32 v137, v137, v0
	v_pk_add_f32 v[50:51], v[50:51], v[0:1] op_sel_hi:[1,0] neg_lo:[0,1] neg_hi:[0,1]
	v_pk_add_f32 v[52:53], v[52:53], v[0:1] op_sel_hi:[1,0] neg_lo:[0,1] neg_hi:[0,1]
	v_mul_f32_e32 v34, v34, v138
	v_pk_add_f32 v[54:55], v[54:55], v[0:1] op_sel_hi:[1,0] neg_lo:[0,1] neg_hi:[0,1]
	v_pk_add_f32 v[56:57], v[56:57], v[0:1] op_sel_hi:[1,0] neg_lo:[0,1] neg_hi:[0,1]
	v_pk_add_f32 v[58:59], v[58:59], v[0:1] op_sel_hi:[1,0] neg_lo:[0,1] neg_hi:[0,1]
	v_pk_add_f32 v[60:61], v[60:61], v[0:1] op_sel_hi:[1,0] neg_lo:[0,1] neg_hi:[0,1]
	v_pk_add_f32 v[62:63], v[62:63], v[0:1] op_sel_hi:[1,0] neg_lo:[0,1] neg_hi:[0,1]
	v_pk_add_f32 v[64:65], v[64:65], v[0:1] op_sel_hi:[1,0] neg_lo:[0,1] neg_hi:[0,1]
	v_sub_f32_e32 v81, v81, v0
	v_sub_f32_e32 v80, v80, v0
	v_sub_f32_e32 v79, v79, v0
	v_sub_f32_e32 v78, v78, v0
	v_sub_f32_e32 v77, v77, v0
	v_sub_f32_e32 v76, v76, v0
	v_sub_f32_e32 v75, v75, v0
	v_sub_f32_e32 v74, v74, v0
	v_sub_f32_e32 v73, v73, v0
	v_sub_f32_e32 v72, v72, v0
	v_sub_f32_e32 v71, v71, v0
	v_sub_f32_e32 v70, v70, v0
	v_sub_f32_e32 v69, v69, v0
	v_sub_f32_e32 v68, v68, v0
	v_sub_f32_e32 v67, v67, v0
	v_sub_f32_e32 v66, v66, v0
	v_pk_mul_f32 v[32:33], v[32:33], v[138:139] op_sel_hi:[1,0]
	v_pk_mul_f32 v[30:31], v[30:31], v[138:139] op_sel_hi:[1,0]
	v_pk_mul_f32 v[28:29], v[28:29], v[138:139] op_sel_hi:[1,0]
	v_pk_mul_f32 v[26:27], v[26:27], v[138:139] op_sel_hi:[1,0]
	v_pk_mul_f32 v[24:25], v[24:25], v[138:139] op_sel_hi:[1,0]
	v_pk_mul_f32 v[22:23], v[22:23], v[138:139] op_sel_hi:[1,0]
	v_pk_mul_f32 v[20:21], v[20:21], v[138:139] op_sel_hi:[1,0]
	v_pk_mul_f32 v[18:19], v[18:19], v[138:139] op_sel_hi:[1,0]
	v_pk_mul_f32 v[16:17], v[16:17], v[138:139] op_sel_hi:[1,0]
	v_pk_mul_f32 v[14:15], v[14:15], v[138:139] op_sel_hi:[1,0]
	v_pk_mul_f32 v[12:13], v[12:13], v[138:139] op_sel_hi:[1,0]
	v_pk_mul_f32 v[10:11], v[10:11], v[138:139] op_sel_hi:[1,0]
	v_pk_mul_f32 v[8:9], v[8:9], v[138:139] op_sel_hi:[1,0]
	v_pk_mul_f32 v[6:7], v[6:7], v[138:139] op_sel_hi:[1,0]
	v_pk_mul_f32 v[4:5], v[4:5], v[138:139] op_sel_hi:[1,0]
	v_pk_mul_f32 v[2:3], v[2:3], v[138:139] op_sel_hi:[1,0]

.LBB0_750:
	s_add_i32 s91, s0, 0
	s_lshl_b32 s0, s1, 1
	s_and_b32 s0, s0, -4
	s_add_i32 s68, s0, 0
	s_add_i32 s68, s68, 0x1b000
	s_cmp_le_u32 s77, s73
	v_lshl_add_u32 v120, v132, 2, s91
	s_cselect_b64 s[0:1], -1, 0
	s_cmp_gt_u32 s77, s73
	v_add_u32_e32 v119, s91, v125
	v_add_u32_e32 v118, s91, v126
	v_add_u32_e32 v117, s91, v127
	v_add_u32_e32 v0, s91, v128
	s_cbranch_scc1 .LBB0_753
	s_setprio 1
	v_mov_b32_e32 v50, s68
	ds_read_b32 v58, v50
	v_sub_f32_e32 v59, v110, v116
	ds_read_b128 v[74:77], v120 offset:32832
	ds_read_b128 v[50:53], v120 offset:32768
	ds_read_b128 v[54:57], v120 offset:32800
	s_waitcnt lgkmcnt(0)
	v_sub_f32_e32 v121, v59, v58
	ds_read_b128 v[58:61], v120 offset:32864
	ds_read_b128 v[140:143], v118
	v_sub_f32_e32 v53, v121, v53
	v_sub_f32_e32 v57, v121, v57
	v_sub_f32_e32 v56, v121, v56
	s_waitcnt lgkmcnt(0)
	v_sub_f32_e32 v65, v121, v61
	v_sub_f32_e32 v64, v121, v60
	v_sub_f32_e32 v63, v121, v59
	v_sub_f32_e32 v62, v121, v58
	v_sub_f32_e32 v61, v121, v77
	v_sub_f32_e32 v60, v121, v76
	v_sub_f32_e32 v59, v121, v75
	v_sub_f32_e32 v58, v121, v74
	ds_read_b128 v[74:77], v119
	v_sub_f32_e32 v55, v121, v55
	v_sub_f32_e32 v54, v121, v54
	v_sub_f32_e32 v52, v121, v52
	v_sub_f32_e32 v51, v121, v51
	v_sub_f32_e32 v50, v121, v50
	ds_read_b128 v[66:69], v120 offset:32896
	ds_read_b128 v[70:73], v120 offset:32928
	ds_read_b128 v[136:139], v120 offset:32960
	ds_read_b128 v[78:81], v120 offset:32992
	ds_read_b128 v[144:147], v117
	s_waitcnt lgkmcnt(0)
	v_mfma_f32_32x32x16_bf16 v[50:65], v[74:77], v[88:91], v[50:65]
	ds_read_b128 v[148:151], v0
	v_sub_f32_e32 v77, v121, v139
	v_sub_f32_e32 v76, v121, v138
	v_sub_f32_e32 v75, v121, v137
	v_sub_f32_e32 v74, v121, v136
	v_sub_f32_e32 v81, v121, v81
	v_sub_f32_e32 v80, v121, v80
	v_mfma_f32_32x32x16_bf16 v[50:65], v[140:143], v[92:95], v[50:65]
	ds_read_b128 v[136:139], v119 offset:4096
	v_sub_f32_e32 v79, v121, v79
	v_sub_f32_e32 v78, v121, v78
	v_sub_f32_e32 v73, v121, v73
	v_sub_f32_e32 v72, v121, v72
	v_sub_f32_e32 v71, v121, v71
	v_sub_f32_e32 v70, v121, v70
	v_mfma_f32_32x32x16_bf16 v[50:65], v[144:147], v[96:99], v[50:65]
	v_sub_f32_e32 v69, v121, v69
	v_sub_f32_e32 v68, v121, v68
	v_sub_f32_e32 v67, v121, v67
	v_sub_f32_e32 v66, v121, v66
	ds_read_b128 v[140:143], v118 offset:4096
	s_cmp_lg_u32 s73, s77
	s_waitcnt lgkmcnt(0)
	v_mfma_f32_32x32x16_bf16 v[66:81], v[136:139], v[88:91], v[66:81]
	ds_read_b128 v[136:139], v117 offset:4096
	v_mfma_f32_32x32x16_bf16 v[66:81], v[140:143], v[92:95], v[66:81]
	s_waitcnt lgkmcnt(0)
	v_mfma_f32_32x32x16_bf16 v[66:81], v[136:139], v[96:99], v[66:81]
	ds_read_b128 v[136:139], v0 offset:4096
	s_waitcnt lgkmcnt(0)
	v_mfma_f32_32x32x16_bf16 v[66:81], v[136:139], v[100:103], v[66:81]
	v_mfma_f32_32x32x16_bf16 v[50:65], v[148:151], v[100:103], v[50:65]
	s_cbranch_scc1 .LBB0_753
	s_nop 10
	v_cndmask_b32_e64 v121, v50, v115, s[2:3]
	v_cndmask_b32_e64 v66, v66, v115, s[4:5]
	v_cndmask_b32_e64 v50, v121, v50, s[6:7]
	v_cndmask_b32_e64 v51, v115, v51, s[6:7]
	v_cndmask_b32_e64 v67, v67, v115, s[8:9]
	v_cndmask_b32_e64 v52, v52, v115, s[10:11]
	v_cndmask_b32_e64 v68, v68, v115, s[12:13]
	v_cndmask_b32_e64 v53, v53, v115, s[14:15]
	v_cndmask_b32_e64 v69, v69, v115, s[16:17]
	v_cndmask_b32_e64 v54, v54, v115, s[18:19]
	v_cndmask_b32_e64 v70, v70, v115, s[20:21]
	v_cndmask_b32_e64 v55, v55, v115, s[22:23]
	v_cndmask_b32_e64 v71, v71, v115, s[24:25]
	v_cndmask_b32_e64 v56, v56, v115, s[26:27]
	v_cndmask_b32_e64 v72, v72, v115, s[28:29]
	v_cndmask_b32_e64 v57, v57, v115, s[30:31]
	v_cndmask_b32_e64 v73, v73, v115, s[34:35]
	v_cndmask_b32_e64 v58, v58, v115, s[36:37]
	v_cndmask_b32_e64 v74, v74, v115, s[38:39]
	v_cndmask_b32_e64 v59, v59, v115, s[40:41]
	v_cndmask_b32_e64 v75, v75, v115, s[42:43]
	v_cndmask_b32_e64 v60, v60, v115, s[44:45]
	v_cndmask_b32_e64 v76, v76, v115, s[46:47]
	v_cndmask_b32_e64 v61, v61, v115, s[48:49]
	v_cndmask_b32_e64 v77, v77, v115, s[50:51]
	v_cndmask_b32_e64 v62, v62, v115, s[52:53]
	v_cndmask_b32_e64 v78, v78, v115, s[54:55]
	v_cndmask_b32_e64 v63, v63, v115, s[56:57]
	v_cndmask_b32_e64 v79, v79, v115, s[58:59]
	v_cndmask_b32_e64 v64, v64, v115, s[60:61]
	v_cndmask_b32_e64 v80, v80, v115, s[62:63]
	v_cndmask_b32_e64 v65, v65, v115, s[64:65]
	v_cndmask_b32_e64 v81, v81, v115, s[66:67]
.LBB0_753:
	s_andn2_b64 vcc, exec, s[0:1]
	s_cbranch_vccnz .LBB0_759
	s_setprio 0
	s_nop 8
	v_max_f32_e32 v121, v50, v51
	v_max3_f32 v121, v121, v52, v53
	v_max3_f32 v121, v121, v54, v55
	v_max3_f32 v121, v121, v56, v57
	v_max3_f32 v121, v121, v58, v59
	v_max3_f32 v121, v121, v60, v61
	v_max3_f32 v121, v121, v62, v63
	v_max3_f32 v121, v121, v64, v65
	v_mov_b32_e32 v122, v121
	s_nop 1
	v_permlane32_swap_b32_e32 v121, v122
	v_max_f32_e32 v121, v121, v122
	s_cmp_eq_u32 s70, 0
	s_cselect_b64 s[0:1], -1, 0
	v_cmp_lt_f32_e32 vcc, s95, v121
	s_or_b64 vcc, s[0:1], vcc
	s_cbranch_vccz .LBB0_756
	v_max_f32_e32 v122, v121, v121
	v_max_f32_e32 v122, 0, v122
	v_cndmask_b32_e64 v122, v122, v121, s[0:1]
	v_exp_f32_e64 v121, -v122
	v_add_f32_e32 v116, v116, v122
	v_pk_add_f32 v[50:51], v[50:51], v[122:123] op_sel_hi:[1,0] neg_lo:[0,1] neg_hi:[0,1]
	v_pk_add_f32 v[52:53], v[52:53], v[122:123] op_sel_hi:[1,0] neg_lo:[0,1] neg_hi:[0,1]
	v_cndmask_b32_e64 v136, v121, 1.0, s[0:1]
	v_mul_f32_e32 v34, v34, v136
	v_pk_add_f32 v[54:55], v[54:55], v[122:123] op_sel_hi:[1,0] neg_lo:[0,1] neg_hi:[0,1]
	v_pk_add_f32 v[56:57], v[56:57], v[122:123] op_sel_hi:[1,0] neg_lo:[0,1] neg_hi:[0,1]
	v_pk_add_f32 v[58:59], v[58:59], v[122:123] op_sel_hi:[1,0] neg_lo:[0,1] neg_hi:[0,1]
	v_pk_add_f32 v[60:61], v[60:61], v[122:123] op_sel_hi:[1,0] neg_lo:[0,1] neg_hi:[0,1]
	v_pk_add_f32 v[62:63], v[62:63], v[122:123] op_sel_hi:[1,0] neg_lo:[0,1] neg_hi:[0,1]
	v_pk_add_f32 v[64:65], v[64:65], v[122:123] op_sel_hi:[1,0] neg_lo:[0,1] neg_hi:[0,1]
	v_sub_f32_e32 v81, v81, v122
	v_sub_f32_e32 v80, v80, v122
	v_sub_f32_e32 v79, v79, v122
	v_sub_f32_e32 v78, v78, v122
	v_sub_f32_e32 v77, v77, v122
	v_sub_f32_e32 v76, v76, v122
	v_sub_f32_e32 v75, v75, v122
	v_sub_f32_e32 v74, v74, v122
	v_sub_f32_e32 v73, v73, v122
	v_sub_f32_e32 v72, v72, v122
	v_sub_f32_e32 v71, v71, v122
	v_sub_f32_e32 v70, v70, v122
	v_sub_f32_e32 v69, v69, v122
	v_sub_f32_e32 v68, v68, v122
	v_sub_f32_e32 v67, v67, v122
	v_sub_f32_e32 v66, v66, v122
	v_pk_mul_f32 v[32:33], v[32:33], v[136:137] op_sel_hi:[1,0]
	v_pk_mul_f32 v[30:31], v[30:31], v[136:137] op_sel_hi:[1,0]
	v_pk_mul_f32 v[28:29], v[28:29], v[136:137] op_sel_hi:[1,0]
	v_pk_mul_f32 v[26:27], v[26:27], v[136:137] op_sel_hi:[1,0]
	v_pk_mul_f32 v[24:25], v[24:25], v[136:137] op_sel_hi:[1,0]
	v_pk_mul_f32 v[22:23], v[22:23], v[136:137] op_sel_hi:[1,0]
	v_pk_mul_f32 v[20:21], v[20:21], v[136:137] op_sel_hi:[1,0]
	v_pk_mul_f32 v[18:19], v[18:19], v[136:137] op_sel_hi:[1,0]
	v_pk_mul_f32 v[16:17], v[16:17], v[136:137] op_sel_hi:[1,0]
	v_pk_mul_f32 v[14:15], v[14:15], v[136:137] op_sel_hi:[1,0]
	v_pk_mul_f32 v[12:13], v[12:13], v[136:137] op_sel_hi:[1,0]
	v_pk_mul_f32 v[10:11], v[10:11], v[136:137] op_sel_hi:[1,0]
	v_pk_mul_f32 v[8:9], v[8:9], v[136:137] op_sel_hi:[1,0]
	v_pk_mul_f32 v[6:7], v[6:7], v[136:137] op_sel_hi:[1,0]
	v_pk_mul_f32 v[4:5], v[4:5], v[136:137] op_sel_hi:[1,0]
	v_pk_mul_f32 v[2:3], v[2:3], v[136:137] op_sel_hi:[1,0]

.LBB0_759:
	s_cmp_lt_u32 s77, s73
	s_cselect_b64 s[0:1], -1, 0
	s_cmp_ge_u32 s77, s73
	s_cbranch_scc1 .LBB0_762
	s_setprio 1
	s_nop 4
	v_mov_b32_e32 v50, s68
	ds_read_b32 v58, v50
	v_sub_f32_e32 v59, v110, v116
	ds_read_b128 v[74:77], v120 offset:33088
	ds_read_b128 v[50:53], v120 offset:33024
	ds_read_b128 v[54:57], v120 offset:33056
	s_waitcnt lgkmcnt(0)
	v_sub_f32_e32 v148, v59, v58
	ds_read_b128 v[58:61], v120 offset:33120
	ds_read_b128 v[66:69], v120 offset:33152
	ds_read_b128 v[70:73], v120 offset:33184
	ds_read_b128 v[136:139], v120 offset:33216
	ds_read_b128 v[78:81], v120 offset:33248
	s_waitcnt lgkmcnt(0)
	v_sub_f32_e32 v65, v148, v61
	v_sub_f32_e32 v64, v148, v60
	v_sub_f32_e32 v63, v148, v59
	v_sub_f32_e32 v62, v148, v58
	v_sub_f32_e32 v61, v148, v77
	v_sub_f32_e32 v60, v148, v76
	v_sub_f32_e32 v59, v148, v75
	v_sub_f32_e32 v58, v148, v74
	ds_read_b128 v[74:77], v119 offset:8192
	v_sub_f32_e32 v57, v148, v57
	v_sub_f32_e32 v56, v148, v56
	v_sub_f32_e32 v55, v148, v55
	v_sub_f32_e32 v54, v148, v54
	v_sub_f32_e32 v53, v148, v53
	v_sub_f32_e32 v52, v148, v52
	v_sub_f32_e32 v51, v148, v51
	v_sub_f32_e32 v50, v148, v50
	ds_read_b128 v[120:123], v118 offset:8192
	ds_read_b128 v[140:143], v117 offset:8192
	s_waitcnt lgkmcnt(0)
	v_mfma_f32_32x32x16_bf16 v[50:65], v[74:77], v[88:91], v[50:65]
	ds_read_b128 v[144:147], v0 offset:8192
	v_sub_f32_e32 v81, v148, v81
	v_sub_f32_e32 v80, v148, v80
	v_sub_f32_e32 v79, v148, v79
	v_sub_f32_e32 v78, v148, v78
	v_sub_f32_e32 v77, v148, v139
	v_sub_f32_e32 v76, v148, v138
	v_mfma_f32_32x32x16_bf16 v[50:65], v[120:123], v[92:95], v[50:65]
	ds_read_b128 v[120:123], v119 offset:12288
	v_sub_f32_e32 v75, v148, v137
	v_sub_f32_e32 v74, v148, v136
	v_sub_f32_e32 v73, v148, v73
	v_sub_f32_e32 v72, v148, v72
	v_sub_f32_e32 v71, v148, v71
	v_sub_f32_e32 v70, v148, v70
	v_mfma_f32_32x32x16_bf16 v[50:65], v[140:143], v[96:99], v[50:65]
	v_sub_f32_e32 v69, v148, v69
	v_sub_f32_e32 v68, v148, v68
	v_sub_f32_e32 v67, v148, v67
	v_sub_f32_e32 v66, v148, v66
	ds_read_b128 v[136:139], v118 offset:12288
	s_cmp_lg_u32 s93, s77
	s_waitcnt lgkmcnt(0)
	v_mfma_f32_32x32x16_bf16 v[66:81], v[120:123], v[88:91], v[66:81]
	ds_read_b128 v[118:121], v117 offset:12288
	v_mfma_f32_32x32x16_bf16 v[66:81], v[136:139], v[92:95], v[66:81]
	s_waitcnt lgkmcnt(0)
	v_mfma_f32_32x32x16_bf16 v[66:81], v[118:121], v[96:99], v[66:81]
	ds_read_b128 v[118:121], v0 offset:12288
	s_waitcnt lgkmcnt(0)
	v_mfma_f32_32x32x16_bf16 v[66:81], v[118:121], v[100:103], v[66:81]
	v_mfma_f32_32x32x16_bf16 v[50:65], v[144:147], v[100:103], v[50:65]
	s_cbranch_scc1 .LBB0_762
	s_nop 10
	v_cndmask_b32_e64 v0, v50, v115, s[2:3]
	v_cndmask_b32_e64 v66, v66, v115, s[4:5]
	v_cndmask_b32_e64 v50, v0, v50, s[6:7]
	v_cndmask_b32_e64 v51, v115, v51, s[6:7]
	v_cndmask_b32_e64 v67, v67, v115, s[8:9]
	v_cndmask_b32_e64 v52, v52, v115, s[10:11]
	v_cndmask_b32_e64 v68, v68, v115, s[12:13]
	v_cndmask_b32_e64 v53, v53, v115, s[14:15]
	v_cndmask_b32_e64 v69, v69, v115, s[16:17]
	v_cndmask_b32_e64 v54, v54, v115, s[18:19]
	v_cndmask_b32_e64 v70, v70, v115, s[20:21]
	v_cndmask_b32_e64 v55, v55, v115, s[22:23]
	v_cndmask_b32_e64 v71, v71, v115, s[24:25]
	v_cndmask_b32_e64 v56, v56, v115, s[26:27]
	v_cndmask_b32_e64 v72, v72, v115, s[28:29]
	v_cndmask_b32_e64 v57, v57, v115, s[30:31]
	v_cndmask_b32_e64 v73, v73, v115, s[34:35]
	v_cndmask_b32_e64 v58, v58, v115, s[36:37]
	v_cndmask_b32_e64 v74, v74, v115, s[38:39]
	v_cndmask_b32_e64 v59, v59, v115, s[40:41]
	v_cndmask_b32_e64 v75, v75, v115, s[42:43]
	v_cndmask_b32_e64 v60, v60, v115, s[44:45]
	v_cndmask_b32_e64 v76, v76, v115, s[46:47]
	v_cndmask_b32_e64 v61, v61, v115, s[48:49]
	v_cndmask_b32_e64 v77, v77, v115, s[50:51]
	v_cndmask_b32_e64 v62, v62, v115, s[52:53]
	v_cndmask_b32_e64 v78, v78, v115, s[54:55]
	v_cndmask_b32_e64 v63, v63, v115, s[56:57]
	v_cndmask_b32_e64 v79, v79, v115, s[58:59]
	v_cndmask_b32_e64 v64, v64, v115, s[60:61]
	v_cndmask_b32_e64 v80, v80, v115, s[62:63]
	v_cndmask_b32_e64 v65, v65, v115, s[64:65]
	v_cndmask_b32_e64 v81, v81, v115, s[66:67]
.LBB0_762:
	s_andn2_b64 vcc, exec, s[0:1]
	s_cbranch_vccnz .LBB0_768
	s_setprio 0
	s_nop 8
	v_max_f32_e32 v0, v50, v51
	v_max3_f32 v0, v0, v52, v53
	v_max3_f32 v0, v0, v54, v55
	v_max3_f32 v0, v0, v56, v57
	v_max3_f32 v0, v0, v58, v59
	v_max3_f32 v0, v0, v60, v61
	v_max3_f32 v0, v0, v62, v63
	v_max3_f32 v0, v0, v64, v65
	v_mov_b32_e32 v117, v0
	s_nop 1
	v_permlane32_swap_b32_e32 v0, v117
	v_max_f32_e32 v0, v0, v117
	v_cmp_lt_f32_e32 vcc, s95, v0
	s_cbranch_vccz .LBB0_765
	v_max_f32_e32 v0, v0, v0
	v_max_f32_e32 v0, 0, v0
	v_exp_f32_e64 v118, -v0
	v_add_f32_e32 v116, v116, v0
	v_pk_add_f32 v[50:51], v[50:51], v[0:1] op_sel_hi:[1,0] neg_lo:[0,1] neg_hi:[0,1]
	v_pk_add_f32 v[52:53], v[52:53], v[0:1] op_sel_hi:[1,0] neg_lo:[0,1] neg_hi:[0,1]
	v_mul_f32_e32 v34, v34, v118
	v_pk_add_f32 v[54:55], v[54:55], v[0:1] op_sel_hi:[1,0] neg_lo:[0,1] neg_hi:[0,1]
	v_pk_add_f32 v[56:57], v[56:57], v[0:1] op_sel_hi:[1,0] neg_lo:[0,1] neg_hi:[0,1]
	v_pk_add_f32 v[58:59], v[58:59], v[0:1] op_sel_hi:[1,0] neg_lo:[0,1] neg_hi:[0,1]
	v_pk_add_f32 v[60:61], v[60:61], v[0:1] op_sel_hi:[1,0] neg_lo:[0,1] neg_hi:[0,1]
	v_pk_add_f32 v[62:63], v[62:63], v[0:1] op_sel_hi:[1,0] neg_lo:[0,1] neg_hi:[0,1]
	v_pk_add_f32 v[64:65], v[64:65], v[0:1] op_sel_hi:[1,0] neg_lo:[0,1] neg_hi:[0,1]
	v_sub_f32_e32 v81, v81, v0
	v_sub_f32_e32 v80, v80, v0
	v_sub_f32_e32 v79, v79, v0
	v_sub_f32_e32 v78, v78, v0
	v_sub_f32_e32 v77, v77, v0
	v_sub_f32_e32 v76, v76, v0
	v_sub_f32_e32 v75, v75, v0
	v_sub_f32_e32 v74, v74, v0
	v_sub_f32_e32 v73, v73, v0
	v_sub_f32_e32 v72, v72, v0
	v_sub_f32_e32 v71, v71, v0
	v_sub_f32_e32 v70, v70, v0
	v_sub_f32_e32 v69, v69, v0
	v_sub_f32_e32 v68, v68, v0
	v_sub_f32_e32 v67, v67, v0
	v_sub_f32_e32 v66, v66, v0
	v_pk_mul_f32 v[32:33], v[32:33], v[118:119] op_sel_hi:[1,0]
	v_pk_mul_f32 v[30:31], v[30:31], v[118:119] op_sel_hi:[1,0]
	v_pk_mul_f32 v[28:29], v[28:29], v[118:119] op_sel_hi:[1,0]
	v_pk_mul_f32 v[26:27], v[26:27], v[118:119] op_sel_hi:[1,0]
	v_pk_mul_f32 v[24:25], v[24:25], v[118:119] op_sel_hi:[1,0]
	v_pk_mul_f32 v[22:23], v[22:23], v[118:119] op_sel_hi:[1,0]
	v_pk_mul_f32 v[20:21], v[20:21], v[118:119] op_sel_hi:[1,0]
	v_pk_mul_f32 v[18:19], v[18:19], v[118:119] op_sel_hi:[1,0]
	v_pk_mul_f32 v[16:17], v[16:17], v[118:119] op_sel_hi:[1,0]
	v_pk_mul_f32 v[14:15], v[14:15], v[118:119] op_sel_hi:[1,0]
	v_pk_mul_f32 v[12:13], v[12:13], v[118:119] op_sel_hi:[1,0]
	v_pk_mul_f32 v[10:11], v[10:11], v[118:119] op_sel_hi:[1,0]
	v_pk_mul_f32 v[8:9], v[8:9], v[118:119] op_sel_hi:[1,0]
	v_pk_mul_f32 v[6:7], v[6:7], v[118:119] op_sel_hi:[1,0]
	v_pk_mul_f32 v[4:5], v[4:5], v[118:119] op_sel_hi:[1,0]
	v_pk_mul_f32 v[2:3], v[2:3], v[118:119] op_sel_hi:[1,0]

.LBB0_778:
	s_add_i32 s91, s0, 0
	s_lshl_b32 s0, s1, 1
	s_and_b32 s0, s0, -4
	s_add_i32 s68, s0, 0
	s_add_i32 s68, s68, 0x1b000
	s_cmp_le_u32 s77, s71
	v_lshl_add_u32 v141, v132, 2, s91
	s_cselect_b64 s[0:1], -1, 0
	s_cmp_gt_u32 s77, s71
	v_add_u32_e32 v140, s91, v125
	v_add_u32_e32 v139, s91, v126
	v_add_u32_e32 v138, s91, v127
	v_add_u32_e32 v2, s91, v128
	s_cbranch_scc1 .LBB0_781
	s_setprio 1
	v_mov_b32_e32 v52, s68
	ds_read_b32 v60, v52
	v_sub_f32_e32 v61, v113, v137
	ds_read_b128 v[76:79], v141 offset:32832
	ds_read_b128 v[52:55], v141 offset:32768
	ds_read_b128 v[56:59], v141 offset:32800
	s_waitcnt lgkmcnt(0)
	v_sub_f32_e32 v158, v61, v60
	ds_read_b128 v[60:63], v141 offset:32864
	ds_read_b128 v[146:149], v139
	v_sub_f32_e32 v55, v158, v55
	v_sub_f32_e32 v59, v158, v59
	v_sub_f32_e32 v58, v158, v58
	s_waitcnt lgkmcnt(0)
	v_sub_f32_e32 v67, v158, v63
	v_sub_f32_e32 v66, v158, v62
	v_sub_f32_e32 v65, v158, v61
	v_sub_f32_e32 v64, v158, v60
	v_sub_f32_e32 v63, v158, v79
	v_sub_f32_e32 v62, v158, v78
	v_sub_f32_e32 v61, v158, v77
	v_sub_f32_e32 v60, v158, v76
	ds_read_b128 v[76:79], v140
	v_sub_f32_e32 v57, v158, v57
	v_sub_f32_e32 v56, v158, v56
	v_sub_f32_e32 v54, v158, v54
	v_sub_f32_e32 v53, v158, v53
	v_sub_f32_e32 v52, v158, v52
	ds_read_b128 v[68:71], v141 offset:32896
	ds_read_b128 v[72:75], v141 offset:32928
	ds_read_b128 v[142:145], v141 offset:32960
	ds_read_b128 v[80:83], v141 offset:32992
	ds_read_b128 v[150:153], v138
	s_waitcnt lgkmcnt(0)
	v_mfma_f32_32x32x16_bf16 v[52:67], v[76:79], v[88:91], v[52:67]
	ds_read_b128 v[154:157], v2
	v_sub_f32_e32 v79, v158, v145
	v_sub_f32_e32 v78, v158, v144
	v_sub_f32_e32 v77, v158, v143
	v_sub_f32_e32 v76, v158, v142
	v_sub_f32_e32 v83, v158, v83
	v_sub_f32_e32 v82, v158, v82
	v_mfma_f32_32x32x16_bf16 v[52:67], v[146:149], v[92:95], v[52:67]
	ds_read_b128 v[142:145], v140 offset:4096
	v_sub_f32_e32 v81, v158, v81
	v_sub_f32_e32 v80, v158, v80
	v_sub_f32_e32 v75, v158, v75
	v_sub_f32_e32 v74, v158, v74
	v_sub_f32_e32 v73, v158, v73
	v_sub_f32_e32 v72, v158, v72
	v_mfma_f32_32x32x16_bf16 v[52:67], v[150:153], v[96:99], v[52:67]
	v_sub_f32_e32 v71, v158, v71
	v_sub_f32_e32 v70, v158, v70
	v_sub_f32_e32 v69, v158, v69
	v_sub_f32_e32 v68, v158, v68
	ds_read_b128 v[146:149], v139 offset:4096
	s_cmp_lg_u32 s33, s77
	s_waitcnt lgkmcnt(0)
	v_mfma_f32_32x32x16_bf16 v[68:83], v[142:145], v[88:91], v[68:83]
	ds_read_b128 v[142:145], v138 offset:4096
	v_mfma_f32_32x32x16_bf16 v[68:83], v[146:149], v[92:95], v[68:83]
	s_waitcnt lgkmcnt(0)
	v_mfma_f32_32x32x16_bf16 v[68:83], v[142:145], v[96:99], v[68:83]
	ds_read_b128 v[142:145], v2 offset:4096
	s_waitcnt lgkmcnt(0)
	v_mfma_f32_32x32x16_bf16 v[68:83], v[142:145], v[100:103], v[68:83]
	v_mfma_f32_32x32x16_bf16 v[52:67], v[154:157], v[100:103], v[52:67]
	s_cbranch_scc1 .LBB0_781
	s_nop 10
	v_cndmask_b32_e64 v142, v52, v123, s[2:3]
	v_cndmask_b32_e64 v68, v68, v123, s[4:5]
	v_cndmask_b32_e64 v52, v142, v52, s[6:7]
	v_cndmask_b32_e64 v53, v123, v53, s[6:7]
	v_cndmask_b32_e64 v69, v69, v123, s[8:9]
	v_cndmask_b32_e64 v54, v54, v123, s[10:11]
	v_cndmask_b32_e64 v70, v70, v123, s[12:13]
	v_cndmask_b32_e64 v55, v55, v123, s[14:15]
	v_cndmask_b32_e64 v71, v71, v123, s[16:17]
	v_cndmask_b32_e64 v56, v56, v123, s[18:19]
	v_cndmask_b32_e64 v72, v72, v123, s[20:21]
	v_cndmask_b32_e64 v57, v57, v123, s[22:23]
	v_cndmask_b32_e64 v73, v73, v123, s[24:25]
	v_cndmask_b32_e64 v58, v58, v123, s[26:27]
	v_cndmask_b32_e64 v74, v74, v123, s[28:29]
	v_cndmask_b32_e64 v59, v59, v123, s[30:31]
	v_cndmask_b32_e64 v75, v75, v123, s[34:35]
	v_cndmask_b32_e64 v60, v60, v123, s[36:37]
	v_cndmask_b32_e64 v76, v76, v123, s[38:39]
	v_cndmask_b32_e64 v61, v61, v123, s[40:41]
	v_cndmask_b32_e64 v77, v77, v123, s[42:43]
	v_cndmask_b32_e64 v62, v62, v123, s[44:45]
	v_cndmask_b32_e64 v78, v78, v123, s[46:47]
	v_cndmask_b32_e64 v63, v63, v123, s[48:49]
	v_cndmask_b32_e64 v79, v79, v123, s[50:51]
	v_cndmask_b32_e64 v64, v64, v123, s[52:53]
	v_cndmask_b32_e64 v80, v80, v123, s[54:55]
	v_cndmask_b32_e64 v65, v65, v123, s[56:57]
	v_cndmask_b32_e64 v81, v81, v123, s[58:59]
	v_cndmask_b32_e64 v66, v66, v123, s[60:61]
	v_cndmask_b32_e64 v82, v82, v123, s[62:63]
	v_cndmask_b32_e64 v67, v67, v123, s[64:65]
	v_cndmask_b32_e64 v83, v83, v123, s[66:67]
.LBB0_781:
	s_andn2_b64 vcc, exec, s[0:1]
	s_cbranch_vccnz .LBB0_787
	s_setprio 0
	s_nop 8
	v_max_f32_e32 v142, v52, v53
	v_max3_f32 v142, v142, v54, v55
	v_max3_f32 v142, v142, v56, v57
	v_max3_f32 v142, v142, v58, v59
	v_max3_f32 v142, v142, v60, v61
	v_max3_f32 v142, v142, v62, v63
	v_max3_f32 v142, v142, v64, v65
	v_max3_f32 v142, v142, v66, v67
	v_mov_b32_e32 v143, v142
	s_nop 1
	v_permlane32_swap_b32_e32 v142, v143
	v_max_f32_e32 v142, v142, v143
	s_cmp_eq_u32 s95, 0
	s_cselect_b64 s[0:1], -1, 0
	v_cmp_lt_f32_e32 vcc, s94, v142
	s_or_b64 vcc, s[0:1], vcc
	s_cbranch_vccz .LBB0_784
	v_max_f32_e32 v143, v142, v142
	v_max_f32_e32 v143, 0, v143
	v_cndmask_b32_e64 v142, v143, v142, s[0:1]
	v_exp_f32_e64 v143, -v142
	v_add_f32_e32 v137, v137, v142
	v_sub_f32_e32 v83, v83, v142
	v_sub_f32_e32 v82, v82, v142
	v_cndmask_b32_e64 v144, v143, 1.0, s[0:1]
	v_pk_add_f32 v[52:53], v[52:53], v[142:143] op_sel_hi:[1,0] neg_lo:[0,1] neg_hi:[0,1]
	v_pk_add_f32 v[54:55], v[54:55], v[142:143] op_sel_hi:[1,0] neg_lo:[0,1] neg_hi:[0,1]
	v_mul_f32_e32 v36, v36, v144
	v_pk_add_f32 v[56:57], v[56:57], v[142:143] op_sel_hi:[1,0] neg_lo:[0,1] neg_hi:[0,1]
	v_pk_add_f32 v[58:59], v[58:59], v[142:143] op_sel_hi:[1,0] neg_lo:[0,1] neg_hi:[0,1]
	v_pk_add_f32 v[60:61], v[60:61], v[142:143] op_sel_hi:[1,0] neg_lo:[0,1] neg_hi:[0,1]
	v_pk_add_f32 v[62:63], v[62:63], v[142:143] op_sel_hi:[1,0] neg_lo:[0,1] neg_hi:[0,1]
	v_pk_add_f32 v[64:65], v[64:65], v[142:143] op_sel_hi:[1,0] neg_lo:[0,1] neg_hi:[0,1]
	v_pk_add_f32 v[66:67], v[66:67], v[142:143] op_sel_hi:[1,0] neg_lo:[0,1] neg_hi:[0,1]
	v_sub_f32_e32 v81, v81, v142
	v_sub_f32_e32 v80, v80, v142
	v_sub_f32_e32 v79, v79, v142
	v_sub_f32_e32 v78, v78, v142
	v_sub_f32_e32 v77, v77, v142
	v_sub_f32_e32 v76, v76, v142
	v_sub_f32_e32 v75, v75, v142
	v_sub_f32_e32 v74, v74, v142
	v_sub_f32_e32 v73, v73, v142
	v_sub_f32_e32 v72, v72, v142
	v_sub_f32_e32 v71, v71, v142
	v_sub_f32_e32 v70, v70, v142
	v_sub_f32_e32 v69, v69, v142
	v_sub_f32_e32 v68, v68, v142
	v_pk_mul_f32 v[34:35], v[34:35], v[144:145] op_sel_hi:[1,0]
	v_pk_mul_f32 v[32:33], v[32:33], v[144:145] op_sel_hi:[1,0]
	v_pk_mul_f32 v[30:31], v[30:31], v[144:145] op_sel_hi:[1,0]
	v_pk_mul_f32 v[28:29], v[28:29], v[144:145] op_sel_hi:[1,0]
	v_pk_mul_f32 v[26:27], v[26:27], v[144:145] op_sel_hi:[1,0]
	v_pk_mul_f32 v[24:25], v[24:25], v[144:145] op_sel_hi:[1,0]
	v_pk_mul_f32 v[22:23], v[22:23], v[144:145] op_sel_hi:[1,0]
	v_pk_mul_f32 v[20:21], v[20:21], v[144:145] op_sel_hi:[1,0]
	v_pk_mul_f32 v[18:19], v[18:19], v[144:145] op_sel_hi:[1,0]
	v_pk_mul_f32 v[16:17], v[16:17], v[144:145] op_sel_hi:[1,0]
	v_pk_mul_f32 v[14:15], v[14:15], v[144:145] op_sel_hi:[1,0]
	v_pk_mul_f32 v[12:13], v[12:13], v[144:145] op_sel_hi:[1,0]
	v_pk_mul_f32 v[10:11], v[10:11], v[144:145] op_sel_hi:[1,0]
	v_pk_mul_f32 v[8:9], v[8:9], v[144:145] op_sel_hi:[1,0]
	v_pk_mul_f32 v[6:7], v[6:7], v[144:145] op_sel_hi:[1,0]
	v_pk_mul_f32 v[4:5], v[4:5], v[144:145] op_sel_hi:[1,0]

.LBB0_787:
	s_cmp_lt_u32 s77, s71
	s_cselect_b64 s[0:1], -1, 0
	s_cmp_ge_u32 s77, s71
	s_cbranch_scc1 .LBB0_790
	s_setprio 1
	s_nop 4
	v_mov_b32_e32 v52, s68
	ds_read_b32 v60, v52
	v_sub_f32_e32 v61, v113, v137
	ds_read_b128 v[76:79], v141 offset:33088
	ds_read_b128 v[52:55], v141 offset:33024
	ds_read_b128 v[56:59], v141 offset:33056
	s_waitcnt lgkmcnt(0)
	v_sub_f32_e32 v158, v61, v60
	ds_read_b128 v[60:63], v141 offset:33120
	ds_read_b128 v[146:149], v139 offset:8192
	v_sub_f32_e32 v55, v158, v55
	v_sub_f32_e32 v59, v158, v59
	v_sub_f32_e32 v58, v158, v58
	s_waitcnt lgkmcnt(0)
	v_sub_f32_e32 v67, v158, v63
	v_sub_f32_e32 v66, v158, v62
	v_sub_f32_e32 v65, v158, v61
	v_sub_f32_e32 v64, v158, v60
	v_sub_f32_e32 v63, v158, v79
	v_sub_f32_e32 v62, v158, v78
	v_sub_f32_e32 v61, v158, v77
	v_sub_f32_e32 v60, v158, v76
	ds_read_b128 v[76:79], v140 offset:8192
	v_sub_f32_e32 v57, v158, v57
	v_sub_f32_e32 v56, v158, v56
	v_sub_f32_e32 v54, v158, v54
	v_sub_f32_e32 v53, v158, v53
	v_sub_f32_e32 v52, v158, v52
	ds_read_b128 v[68:71], v141 offset:33152
	ds_read_b128 v[72:75], v141 offset:33184
	ds_read_b128 v[142:145], v141 offset:33216
	ds_read_b128 v[80:83], v141 offset:33248
	ds_read_b128 v[150:153], v138 offset:8192
	s_waitcnt lgkmcnt(0)
	v_mfma_f32_32x32x16_bf16 v[52:67], v[76:79], v[88:91], v[52:67]
	ds_read_b128 v[154:157], v2 offset:8192
	v_sub_f32_e32 v77, v158, v143
	v_sub_f32_e32 v76, v158, v142
	v_sub_f32_e32 v83, v158, v83
	v_sub_f32_e32 v82, v158, v82
	v_sub_f32_e32 v81, v158, v81
	v_sub_f32_e32 v80, v158, v80
	v_mfma_f32_32x32x16_bf16 v[52:67], v[146:149], v[92:95], v[52:67]
	ds_read_b128 v[140:143], v140 offset:12288
	v_sub_f32_e32 v79, v158, v145
	v_sub_f32_e32 v78, v158, v144
	v_sub_f32_e32 v75, v158, v75
	v_sub_f32_e32 v74, v158, v74
	v_sub_f32_e32 v73, v158, v73
	v_sub_f32_e32 v72, v158, v72
	v_mfma_f32_32x32x16_bf16 v[52:67], v[150:153], v[96:99], v[52:67]
	v_sub_f32_e32 v71, v158, v71
	v_sub_f32_e32 v70, v158, v70
	v_sub_f32_e32 v69, v158, v69
	v_sub_f32_e32 v68, v158, v68
	ds_read_b128 v[144:147], v139 offset:12288
	s_cmp_lg_u32 s76, s77
	s_waitcnt lgkmcnt(0)
	v_mfma_f32_32x32x16_bf16 v[68:83], v[140:143], v[88:91], v[68:83]
	ds_read_b128 v[138:141], v138 offset:12288
	v_mfma_f32_32x32x16_bf16 v[68:83], v[144:147], v[92:95], v[68:83]
	s_waitcnt lgkmcnt(0)
	v_mfma_f32_32x32x16_bf16 v[68:83], v[138:141], v[96:99], v[68:83]
	ds_read_b128 v[138:141], v2 offset:12288
	s_waitcnt lgkmcnt(0)
	v_mfma_f32_32x32x16_bf16 v[68:83], v[138:141], v[100:103], v[68:83]
	v_mfma_f32_32x32x16_bf16 v[52:67], v[154:157], v[100:103], v[52:67]
	s_cbranch_scc1 .LBB0_790
	s_nop 10
	v_cndmask_b32_e64 v2, v52, v123, s[2:3]
	v_cndmask_b32_e64 v68, v68, v123, s[4:5]
	v_cndmask_b32_e64 v52, v2, v52, s[6:7]
	v_cndmask_b32_e64 v53, v123, v53, s[6:7]
	v_cndmask_b32_e64 v69, v69, v123, s[8:9]
	v_cndmask_b32_e64 v54, v54, v123, s[10:11]
	v_cndmask_b32_e64 v70, v70, v123, s[12:13]
	v_cndmask_b32_e64 v55, v55, v123, s[14:15]
	v_cndmask_b32_e64 v71, v71, v123, s[16:17]
	v_cndmask_b32_e64 v56, v56, v123, s[18:19]
	v_cndmask_b32_e64 v72, v72, v123, s[20:21]
	v_cndmask_b32_e64 v57, v57, v123, s[22:23]
	v_cndmask_b32_e64 v73, v73, v123, s[24:25]
	v_cndmask_b32_e64 v58, v58, v123, s[26:27]
	v_cndmask_b32_e64 v74, v74, v123, s[28:29]
	v_cndmask_b32_e64 v59, v59, v123, s[30:31]
	v_cndmask_b32_e64 v75, v75, v123, s[34:35]
	v_cndmask_b32_e64 v60, v60, v123, s[36:37]
	v_cndmask_b32_e64 v76, v76, v123, s[38:39]
	v_cndmask_b32_e64 v61, v61, v123, s[40:41]
	v_cndmask_b32_e64 v77, v77, v123, s[42:43]
	v_cndmask_b32_e64 v62, v62, v123, s[44:45]
	v_cndmask_b32_e64 v78, v78, v123, s[46:47]
	v_cndmask_b32_e64 v63, v63, v123, s[48:49]
	v_cndmask_b32_e64 v79, v79, v123, s[50:51]
	v_cndmask_b32_e64 v64, v64, v123, s[52:53]
	v_cndmask_b32_e64 v80, v80, v123, s[54:55]
	v_cndmask_b32_e64 v65, v65, v123, s[56:57]
	v_cndmask_b32_e64 v81, v81, v123, s[58:59]
	v_cndmask_b32_e64 v66, v66, v123, s[60:61]
	v_cndmask_b32_e64 v82, v82, v123, s[62:63]
	v_cndmask_b32_e64 v67, v67, v123, s[64:65]
	v_cndmask_b32_e64 v83, v83, v123, s[66:67]
.LBB0_790:
	s_andn2_b64 vcc, exec, s[0:1]
	s_cbranch_vccnz .LBB0_796
	s_setprio 0
	s_nop 8
	v_max_f32_e32 v2, v52, v53
	v_max3_f32 v2, v2, v54, v55
	v_max3_f32 v2, v2, v56, v57
	v_max3_f32 v2, v2, v58, v59
	v_max3_f32 v2, v2, v60, v61
	v_max3_f32 v2, v2, v62, v63
	v_max3_f32 v2, v2, v64, v65
	v_max3_f32 v2, v2, v66, v67
	v_mov_b32_e32 v138, v2
	s_nop 1
	v_permlane32_swap_b32_e32 v2, v138
	v_max_f32_e32 v2, v2, v138
	v_cmp_lt_f32_e32 vcc, s94, v2
	s_cbranch_vccz .LBB0_793
	v_max_f32_e32 v2, v2, v2
	v_max_f32_e32 v2, 0, v2
	v_exp_f32_e64 v138, -v2
	v_add_f32_e32 v137, v137, v2
	v_pk_add_f32 v[52:53], v[52:53], v[2:3] op_sel_hi:[1,0] neg_lo:[0,1] neg_hi:[0,1]
	v_pk_add_f32 v[54:55], v[54:55], v[2:3] op_sel_hi:[1,0] neg_lo:[0,1] neg_hi:[0,1]
	v_mul_f32_e32 v36, v36, v138
	v_pk_add_f32 v[56:57], v[56:57], v[2:3] op_sel_hi:[1,0] neg_lo:[0,1] neg_hi:[0,1]
	v_pk_add_f32 v[58:59], v[58:59], v[2:3] op_sel_hi:[1,0] neg_lo:[0,1] neg_hi:[0,1]
	v_pk_add_f32 v[60:61], v[60:61], v[2:3] op_sel_hi:[1,0] neg_lo:[0,1] neg_hi:[0,1]
	v_pk_add_f32 v[62:63], v[62:63], v[2:3] op_sel_hi:[1,0] neg_lo:[0,1] neg_hi:[0,1]
	v_pk_add_f32 v[64:65], v[64:65], v[2:3] op_sel_hi:[1,0] neg_lo:[0,1] neg_hi:[0,1]
	v_pk_add_f32 v[66:67], v[66:67], v[2:3] op_sel_hi:[1,0] neg_lo:[0,1] neg_hi:[0,1]
	v_sub_f32_e32 v83, v83, v2
	v_sub_f32_e32 v82, v82, v2
	v_sub_f32_e32 v81, v81, v2
	v_sub_f32_e32 v80, v80, v2
	v_sub_f32_e32 v79, v79, v2
	v_sub_f32_e32 v78, v78, v2
	v_sub_f32_e32 v77, v77, v2
	v_sub_f32_e32 v76, v76, v2
	v_sub_f32_e32 v75, v75, v2
	v_sub_f32_e32 v74, v74, v2
	v_sub_f32_e32 v73, v73, v2
	v_sub_f32_e32 v72, v72, v2
	v_sub_f32_e32 v71, v71, v2
	v_sub_f32_e32 v70, v70, v2
	v_sub_f32_e32 v69, v69, v2
	v_sub_f32_e32 v68, v68, v2
	v_pk_mul_f32 v[34:35], v[34:35], v[138:139] op_sel_hi:[1,0]
	v_pk_mul_f32 v[32:33], v[32:33], v[138:139] op_sel_hi:[1,0]
	v_pk_mul_f32 v[30:31], v[30:31], v[138:139] op_sel_hi:[1,0]
	v_pk_mul_f32 v[28:29], v[28:29], v[138:139] op_sel_hi:[1,0]
	v_pk_mul_f32 v[26:27], v[26:27], v[138:139] op_sel_hi:[1,0]
	v_pk_mul_f32 v[24:25], v[24:25], v[138:139] op_sel_hi:[1,0]
	v_pk_mul_f32 v[22:23], v[22:23], v[138:139] op_sel_hi:[1,0]
	v_pk_mul_f32 v[20:21], v[20:21], v[138:139] op_sel_hi:[1,0]
	v_pk_mul_f32 v[18:19], v[18:19], v[138:139] op_sel_hi:[1,0]
	v_pk_mul_f32 v[16:17], v[16:17], v[138:139] op_sel_hi:[1,0]
	v_pk_mul_f32 v[14:15], v[14:15], v[138:139] op_sel_hi:[1,0]
	v_pk_mul_f32 v[12:13], v[12:13], v[138:139] op_sel_hi:[1,0]
	v_pk_mul_f32 v[10:11], v[10:11], v[138:139] op_sel_hi:[1,0]
	v_pk_mul_f32 v[8:9], v[8:9], v[138:139] op_sel_hi:[1,0]
	v_pk_mul_f32 v[6:7], v[6:7], v[138:139] op_sel_hi:[1,0]
	v_pk_mul_f32 v[4:5], v[4:5], v[138:139] op_sel_hi:[1,0]

.LBB0_806:
	s_add_i32 s95, s0, 0
	s_lshl_b32 s0, s1, 1
	s_and_b32 s0, s0, -4
	s_add_i32 s68, s0, 0
	s_add_i32 s68, s68, 0x1b000
	s_cmp_le_u32 s77, s73
	v_lshl_add_u32 v141, v132, 2, s95
	s_cselect_b64 s[0:1], -1, 0
	s_cmp_gt_u32 s77, s73
	v_add_u32_e32 v140, s95, v125
	v_add_u32_e32 v139, s95, v126
	v_add_u32_e32 v138, s95, v127
	v_add_u32_e32 v2, s95, v128
	s_cbranch_scc1 .LBB0_809
	s_setprio 1
	v_mov_b32_e32 v52, s68
	ds_read_b32 v60, v52
	v_sub_f32_e32 v61, v1, v137
	ds_read_b128 v[76:79], v141 offset:32832
	ds_read_b128 v[52:55], v141 offset:32768
	ds_read_b128 v[56:59], v141 offset:32800
	s_waitcnt lgkmcnt(0)
	v_sub_f32_e32 v158, v61, v60
	ds_read_b128 v[60:63], v141 offset:32864
	ds_read_b128 v[146:149], v139
	v_sub_f32_e32 v55, v158, v55
	v_sub_f32_e32 v59, v158, v59
	v_sub_f32_e32 v58, v158, v58
	s_waitcnt lgkmcnt(0)
	v_sub_f32_e32 v67, v158, v63
	v_sub_f32_e32 v66, v158, v62
	v_sub_f32_e32 v65, v158, v61
	v_sub_f32_e32 v64, v158, v60
	v_sub_f32_e32 v63, v158, v79
	v_sub_f32_e32 v62, v158, v78
	v_sub_f32_e32 v61, v158, v77
	v_sub_f32_e32 v60, v158, v76
	ds_read_b128 v[76:79], v140
	v_sub_f32_e32 v57, v158, v57
	v_sub_f32_e32 v56, v158, v56
	v_sub_f32_e32 v54, v158, v54
	v_sub_f32_e32 v53, v158, v53
	v_sub_f32_e32 v52, v158, v52
	ds_read_b128 v[68:71], v141 offset:32896
	ds_read_b128 v[72:75], v141 offset:32928
	ds_read_b128 v[142:145], v141 offset:32960
	ds_read_b128 v[80:83], v141 offset:32992
	ds_read_b128 v[150:153], v138
	s_waitcnt lgkmcnt(0)
	v_mfma_f32_32x32x16_bf16 v[52:67], v[76:79], v[88:91], v[52:67]
	ds_read_b128 v[154:157], v2
	v_sub_f32_e32 v79, v158, v145
	v_sub_f32_e32 v78, v158, v144
	v_sub_f32_e32 v77, v158, v143
	v_sub_f32_e32 v76, v158, v142
	v_sub_f32_e32 v83, v158, v83
	v_sub_f32_e32 v82, v158, v82
	v_mfma_f32_32x32x16_bf16 v[52:67], v[146:149], v[92:95], v[52:67]
	ds_read_b128 v[142:145], v140 offset:4096
	v_sub_f32_e32 v81, v158, v81
	v_sub_f32_e32 v80, v158, v80
	v_sub_f32_e32 v75, v158, v75
	v_sub_f32_e32 v74, v158, v74
	v_sub_f32_e32 v73, v158, v73
	v_sub_f32_e32 v72, v158, v72
	v_mfma_f32_32x32x16_bf16 v[52:67], v[150:153], v[96:99], v[52:67]
	v_sub_f32_e32 v71, v158, v71
	v_sub_f32_e32 v70, v158, v70
	v_sub_f32_e32 v69, v158, v69
	v_sub_f32_e32 v68, v158, v68
	ds_read_b128 v[146:149], v139 offset:4096
	s_cmp_lg_u32 s73, s77
	s_waitcnt lgkmcnt(0)
	v_mfma_f32_32x32x16_bf16 v[68:83], v[142:145], v[88:91], v[68:83]
	ds_read_b128 v[142:145], v138 offset:4096
	v_mfma_f32_32x32x16_bf16 v[68:83], v[146:149], v[92:95], v[68:83]
	s_waitcnt lgkmcnt(0)
	v_mfma_f32_32x32x16_bf16 v[68:83], v[142:145], v[96:99], v[68:83]
	ds_read_b128 v[142:145], v2 offset:4096
	s_waitcnt lgkmcnt(0)
	v_mfma_f32_32x32x16_bf16 v[68:83], v[142:145], v[100:103], v[68:83]
	v_mfma_f32_32x32x16_bf16 v[52:67], v[154:157], v[100:103], v[52:67]
	s_cbranch_scc1 .LBB0_809
	s_nop 10
	v_cndmask_b32_e64 v142, v52, v121, s[2:3]
	v_cndmask_b32_e64 v68, v68, v121, s[4:5]
	v_cndmask_b32_e64 v52, v142, v52, s[6:7]
	v_cndmask_b32_e64 v53, v121, v53, s[6:7]
	v_cndmask_b32_e64 v69, v69, v121, s[8:9]
	v_cndmask_b32_e64 v54, v54, v121, s[10:11]
	v_cndmask_b32_e64 v70, v70, v121, s[12:13]
	v_cndmask_b32_e64 v55, v55, v121, s[14:15]
	v_cndmask_b32_e64 v71, v71, v121, s[16:17]
	v_cndmask_b32_e64 v56, v56, v121, s[18:19]
	v_cndmask_b32_e64 v72, v72, v121, s[20:21]
	v_cndmask_b32_e64 v57, v57, v121, s[22:23]
	v_cndmask_b32_e64 v73, v73, v121, s[24:25]
	v_cndmask_b32_e64 v58, v58, v121, s[26:27]
	v_cndmask_b32_e64 v74, v74, v121, s[28:29]
	v_cndmask_b32_e64 v59, v59, v121, s[30:31]
	v_cndmask_b32_e64 v75, v75, v121, s[34:35]
	v_cndmask_b32_e64 v60, v60, v121, s[36:37]
	v_cndmask_b32_e64 v76, v76, v121, s[38:39]
	v_cndmask_b32_e64 v61, v61, v121, s[40:41]
	v_cndmask_b32_e64 v77, v77, v121, s[42:43]
	v_cndmask_b32_e64 v62, v62, v121, s[44:45]
	v_cndmask_b32_e64 v78, v78, v121, s[46:47]
	v_cndmask_b32_e64 v63, v63, v121, s[48:49]
	v_cndmask_b32_e64 v79, v79, v121, s[50:51]
	v_cndmask_b32_e64 v64, v64, v121, s[52:53]
	v_cndmask_b32_e64 v80, v80, v121, s[54:55]
	v_cndmask_b32_e64 v65, v65, v121, s[56:57]
	v_cndmask_b32_e64 v81, v81, v121, s[58:59]
	v_cndmask_b32_e64 v66, v66, v121, s[60:61]
	v_cndmask_b32_e64 v82, v82, v121, s[62:63]
	v_cndmask_b32_e64 v67, v67, v121, s[64:65]
	v_cndmask_b32_e64 v83, v83, v121, s[66:67]
.LBB0_809:
	s_andn2_b64 vcc, exec, s[0:1]
	s_cbranch_vccnz .LBB0_815
	s_setprio 0
	s_nop 8
	v_max_f32_e32 v142, v52, v53
	v_max3_f32 v142, v142, v54, v55
	v_max3_f32 v142, v142, v56, v57
	v_max3_f32 v142, v142, v58, v59
	v_max3_f32 v142, v142, v60, v61
	v_max3_f32 v142, v142, v62, v63
	v_max3_f32 v142, v142, v64, v65
	v_max3_f32 v142, v142, v66, v67
	v_mov_b32_e32 v143, v142
	s_nop 1
	v_permlane32_swap_b32_e32 v142, v143
	v_max_f32_e32 v142, v142, v143
	s_cmp_eq_u32 s90, 0
	s_cselect_b64 s[0:1], -1, 0
	v_cmp_lt_f32_e32 vcc, s94, v142
	s_or_b64 vcc, s[0:1], vcc
	s_cbranch_vccz .LBB0_812
	v_max_f32_e32 v143, v142, v142
	v_max_f32_e32 v143, 0, v143
	v_cndmask_b32_e64 v142, v143, v142, s[0:1]
	v_exp_f32_e64 v143, -v142
	v_add_f32_e32 v137, v137, v142
	v_sub_f32_e32 v83, v83, v142
	v_sub_f32_e32 v82, v82, v142
	v_cndmask_b32_e64 v144, v143, 1.0, s[0:1]
	v_pk_add_f32 v[52:53], v[52:53], v[142:143] op_sel_hi:[1,0] neg_lo:[0,1] neg_hi:[0,1]
	v_pk_add_f32 v[54:55], v[54:55], v[142:143] op_sel_hi:[1,0] neg_lo:[0,1] neg_hi:[0,1]
	v_mul_f32_e32 v36, v36, v144
	v_pk_add_f32 v[56:57], v[56:57], v[142:143] op_sel_hi:[1,0] neg_lo:[0,1] neg_hi:[0,1]
	v_pk_add_f32 v[58:59], v[58:59], v[142:143] op_sel_hi:[1,0] neg_lo:[0,1] neg_hi:[0,1]
	v_pk_add_f32 v[60:61], v[60:61], v[142:143] op_sel_hi:[1,0] neg_lo:[0,1] neg_hi:[0,1]
	v_pk_add_f32 v[62:63], v[62:63], v[142:143] op_sel_hi:[1,0] neg_lo:[0,1] neg_hi:[0,1]
	v_pk_add_f32 v[64:65], v[64:65], v[142:143] op_sel_hi:[1,0] neg_lo:[0,1] neg_hi:[0,1]
	v_pk_add_f32 v[66:67], v[66:67], v[142:143] op_sel_hi:[1,0] neg_lo:[0,1] neg_hi:[0,1]
	v_sub_f32_e32 v81, v81, v142
	v_sub_f32_e32 v80, v80, v142
	v_sub_f32_e32 v79, v79, v142
	v_sub_f32_e32 v78, v78, v142
	v_sub_f32_e32 v77, v77, v142
	v_sub_f32_e32 v76, v76, v142
	v_sub_f32_e32 v75, v75, v142
	v_sub_f32_e32 v74, v74, v142
	v_sub_f32_e32 v73, v73, v142
	v_sub_f32_e32 v72, v72, v142
	v_sub_f32_e32 v71, v71, v142
	v_sub_f32_e32 v70, v70, v142
	v_sub_f32_e32 v69, v69, v142
	v_sub_f32_e32 v68, v68, v142
	v_pk_mul_f32 v[34:35], v[34:35], v[144:145] op_sel_hi:[1,0]
	v_pk_mul_f32 v[32:33], v[32:33], v[144:145] op_sel_hi:[1,0]
	v_pk_mul_f32 v[30:31], v[30:31], v[144:145] op_sel_hi:[1,0]
	v_pk_mul_f32 v[28:29], v[28:29], v[144:145] op_sel_hi:[1,0]
	v_pk_mul_f32 v[26:27], v[26:27], v[144:145] op_sel_hi:[1,0]
	v_pk_mul_f32 v[24:25], v[24:25], v[144:145] op_sel_hi:[1,0]
	v_pk_mul_f32 v[22:23], v[22:23], v[144:145] op_sel_hi:[1,0]
	v_pk_mul_f32 v[20:21], v[20:21], v[144:145] op_sel_hi:[1,0]
	v_pk_mul_f32 v[18:19], v[18:19], v[144:145] op_sel_hi:[1,0]
	v_pk_mul_f32 v[16:17], v[16:17], v[144:145] op_sel_hi:[1,0]
	v_pk_mul_f32 v[14:15], v[14:15], v[144:145] op_sel_hi:[1,0]
	v_pk_mul_f32 v[12:13], v[12:13], v[144:145] op_sel_hi:[1,0]
	v_pk_mul_f32 v[10:11], v[10:11], v[144:145] op_sel_hi:[1,0]
	v_pk_mul_f32 v[8:9], v[8:9], v[144:145] op_sel_hi:[1,0]
	v_pk_mul_f32 v[6:7], v[6:7], v[144:145] op_sel_hi:[1,0]
	v_pk_mul_f32 v[4:5], v[4:5], v[144:145] op_sel_hi:[1,0]

.LBB0_815:
	s_cmp_lt_u32 s77, s73
	s_cselect_b64 s[0:1], -1, 0
	s_cmp_ge_u32 s77, s73
	s_cbranch_scc1 .LBB0_818
	s_setprio 1
	s_nop 4
	v_mov_b32_e32 v52, s68
	ds_read_b32 v60, v52
	v_sub_f32_e32 v61, v1, v137
	ds_read_b128 v[76:79], v141 offset:33088
	ds_read_b128 v[52:55], v141 offset:33024
	ds_read_b128 v[56:59], v141 offset:33056
	s_waitcnt lgkmcnt(0)
	v_sub_f32_e32 v158, v61, v60
	ds_read_b128 v[60:63], v141 offset:33120
	ds_read_b128 v[146:149], v139 offset:8192
	v_sub_f32_e32 v55, v158, v55
	v_sub_f32_e32 v59, v158, v59
	v_sub_f32_e32 v58, v158, v58
	s_waitcnt lgkmcnt(0)
	v_sub_f32_e32 v67, v158, v63
	v_sub_f32_e32 v66, v158, v62
	v_sub_f32_e32 v65, v158, v61
	v_sub_f32_e32 v64, v158, v60
	v_sub_f32_e32 v63, v158, v79
	v_sub_f32_e32 v62, v158, v78
	v_sub_f32_e32 v61, v158, v77
	v_sub_f32_e32 v60, v158, v76
	ds_read_b128 v[76:79], v140 offset:8192
	v_sub_f32_e32 v57, v158, v57
	v_sub_f32_e32 v56, v158, v56
	v_sub_f32_e32 v54, v158, v54
	v_sub_f32_e32 v53, v158, v53
	v_sub_f32_e32 v52, v158, v52
	ds_read_b128 v[68:71], v141 offset:33152
	ds_read_b128 v[72:75], v141 offset:33184
	ds_read_b128 v[142:145], v141 offset:33216
	ds_read_b128 v[80:83], v141 offset:33248
	ds_read_b128 v[150:153], v138 offset:8192
	s_waitcnt lgkmcnt(0)
	v_mfma_f32_32x32x16_bf16 v[52:67], v[76:79], v[88:91], v[52:67]
	ds_read_b128 v[154:157], v2 offset:8192
	v_sub_f32_e32 v77, v158, v143
	v_sub_f32_e32 v76, v158, v142
	v_sub_f32_e32 v83, v158, v83
	v_sub_f32_e32 v82, v158, v82
	v_sub_f32_e32 v81, v158, v81
	v_sub_f32_e32 v80, v158, v80
	v_mfma_f32_32x32x16_bf16 v[52:67], v[146:149], v[92:95], v[52:67]
	ds_read_b128 v[140:143], v140 offset:12288
	v_sub_f32_e32 v79, v158, v145
	v_sub_f32_e32 v78, v158, v144
	v_sub_f32_e32 v75, v158, v75
	v_sub_f32_e32 v74, v158, v74
	v_sub_f32_e32 v73, v158, v73
	v_sub_f32_e32 v72, v158, v72
	v_mfma_f32_32x32x16_bf16 v[52:67], v[150:153], v[96:99], v[52:67]
	v_sub_f32_e32 v71, v158, v71
	v_sub_f32_e32 v70, v158, v70
	v_sub_f32_e32 v69, v158, v69
	v_sub_f32_e32 v68, v158, v68
	ds_read_b128 v[144:147], v139 offset:12288
	s_cmp_lg_u32 s92, s77
	s_waitcnt lgkmcnt(0)
	v_mfma_f32_32x32x16_bf16 v[68:83], v[140:143], v[88:91], v[68:83]
	ds_read_b128 v[138:141], v138 offset:12288
	v_mfma_f32_32x32x16_bf16 v[68:83], v[144:147], v[92:95], v[68:83]
	s_waitcnt lgkmcnt(0)
	v_mfma_f32_32x32x16_bf16 v[68:83], v[138:141], v[96:99], v[68:83]
	ds_read_b128 v[138:141], v2 offset:12288
	s_waitcnt lgkmcnt(0)
	v_mfma_f32_32x32x16_bf16 v[68:83], v[138:141], v[100:103], v[68:83]
	v_mfma_f32_32x32x16_bf16 v[52:67], v[154:157], v[100:103], v[52:67]
	s_cbranch_scc1 .LBB0_818
	s_nop 10
	v_cndmask_b32_e64 v2, v52, v121, s[2:3]
	v_cndmask_b32_e64 v68, v68, v121, s[4:5]
	v_cndmask_b32_e64 v52, v2, v52, s[6:7]
	v_cndmask_b32_e64 v53, v121, v53, s[6:7]
	v_cndmask_b32_e64 v69, v69, v121, s[8:9]
	v_cndmask_b32_e64 v54, v54, v121, s[10:11]
	v_cndmask_b32_e64 v70, v70, v121, s[12:13]
	v_cndmask_b32_e64 v55, v55, v121, s[14:15]
	v_cndmask_b32_e64 v71, v71, v121, s[16:17]
	v_cndmask_b32_e64 v56, v56, v121, s[18:19]
	v_cndmask_b32_e64 v72, v72, v121, s[20:21]
	v_cndmask_b32_e64 v57, v57, v121, s[22:23]
	v_cndmask_b32_e64 v73, v73, v121, s[24:25]
	v_cndmask_b32_e64 v58, v58, v121, s[26:27]
	v_cndmask_b32_e64 v74, v74, v121, s[28:29]
	v_cndmask_b32_e64 v59, v59, v121, s[30:31]
	v_cndmask_b32_e64 v75, v75, v121, s[34:35]
	v_cndmask_b32_e64 v60, v60, v121, s[36:37]
	v_cndmask_b32_e64 v76, v76, v121, s[38:39]
	v_cndmask_b32_e64 v61, v61, v121, s[40:41]
	v_cndmask_b32_e64 v77, v77, v121, s[42:43]
	v_cndmask_b32_e64 v62, v62, v121, s[44:45]
	v_cndmask_b32_e64 v78, v78, v121, s[46:47]
	v_cndmask_b32_e64 v63, v63, v121, s[48:49]
	v_cndmask_b32_e64 v79, v79, v121, s[50:51]
	v_cndmask_b32_e64 v64, v64, v121, s[52:53]
	v_cndmask_b32_e64 v80, v80, v121, s[54:55]
	v_cndmask_b32_e64 v65, v65, v121, s[56:57]
	v_cndmask_b32_e64 v81, v81, v121, s[58:59]
	v_cndmask_b32_e64 v66, v66, v121, s[60:61]
	v_cndmask_b32_e64 v82, v82, v121, s[62:63]
	v_cndmask_b32_e64 v67, v67, v121, s[64:65]
	v_cndmask_b32_e64 v83, v83, v121, s[66:67]

.LBB0_834:
	s_add_i32 s91, s0, 0
	s_lshl_b32 s0, s1, 1
	s_and_b32 s0, s0, -4
	s_add_i32 s68, s0, 0
	s_add_i32 s68, s68, 0x1b000
	s_cmp_le_u32 s77, s73
	v_lshl_add_u32 v141, v132, 2, s91
	s_cselect_b64 s[0:1], -1, 0
	s_cmp_gt_u32 s77, s73
	v_add_u32_e32 v140, s91, v125
	v_add_u32_e32 v139, s91, v126
	v_add_u32_e32 v138, s91, v127
	v_add_u32_e32 v2, s91, v128
	s_cbranch_scc1 .LBB0_837
	s_setprio 1
	v_mov_b32_e32 v52, s68
	ds_read_b32 v60, v52
	v_sub_f32_e32 v61, v1, v137
	ds_read_b128 v[76:79], v141 offset:32832
	ds_read_b128 v[52:55], v141 offset:32768
	ds_read_b128 v[56:59], v141 offset:32800
	s_waitcnt lgkmcnt(0)
	v_sub_f32_e32 v158, v61, v60
	ds_read_b128 v[60:63], v141 offset:32864
	ds_read_b128 v[146:149], v139
	v_sub_f32_e32 v55, v158, v55
	v_sub_f32_e32 v59, v158, v59
	v_sub_f32_e32 v58, v158, v58
	s_waitcnt lgkmcnt(0)
	v_sub_f32_e32 v67, v158, v63
	v_sub_f32_e32 v66, v158, v62
	v_sub_f32_e32 v65, v158, v61
	v_sub_f32_e32 v64, v158, v60
	v_sub_f32_e32 v63, v158, v79
	v_sub_f32_e32 v62, v158, v78
	v_sub_f32_e32 v61, v158, v77
	v_sub_f32_e32 v60, v158, v76
	ds_read_b128 v[76:79], v140
	v_sub_f32_e32 v57, v158, v57
	v_sub_f32_e32 v56, v158, v56
	v_sub_f32_e32 v54, v158, v54
	v_sub_f32_e32 v53, v158, v53
	v_sub_f32_e32 v52, v158, v52
	ds_read_b128 v[68:71], v141 offset:32896
	ds_read_b128 v[72:75], v141 offset:32928
	ds_read_b128 v[142:145], v141 offset:32960
	ds_read_b128 v[80:83], v141 offset:32992
	ds_read_b128 v[150:153], v138
	s_waitcnt lgkmcnt(0)
	v_mfma_f32_32x32x16_bf16 v[52:67], v[76:79], v[88:91], v[52:67]
	ds_read_b128 v[154:157], v2
	v_sub_f32_e32 v79, v158, v145
	v_sub_f32_e32 v78, v158, v144
	v_sub_f32_e32 v77, v158, v143
	v_sub_f32_e32 v76, v158, v142
	v_sub_f32_e32 v83, v158, v83
	v_sub_f32_e32 v82, v158, v82
	v_mfma_f32_32x32x16_bf16 v[52:67], v[146:149], v[92:95], v[52:67]
	ds_read_b128 v[142:145], v140 offset:4096
	v_sub_f32_e32 v81, v158, v81
	v_sub_f32_e32 v80, v158, v80
	v_sub_f32_e32 v75, v158, v75
	v_sub_f32_e32 v74, v158, v74
	v_sub_f32_e32 v73, v158, v73
	v_sub_f32_e32 v72, v158, v72
	v_mfma_f32_32x32x16_bf16 v[52:67], v[150:153], v[96:99], v[52:67]
	v_sub_f32_e32 v71, v158, v71
	v_sub_f32_e32 v70, v158, v70
	v_sub_f32_e32 v69, v158, v69
	v_sub_f32_e32 v68, v158, v68
	ds_read_b128 v[146:149], v139 offset:4096
	s_cmp_lg_u32 s76, s77
	s_waitcnt lgkmcnt(0)
	v_mfma_f32_32x32x16_bf16 v[68:83], v[142:145], v[88:91], v[68:83]
	ds_read_b128 v[142:145], v138 offset:4096
	v_mfma_f32_32x32x16_bf16 v[68:83], v[146:149], v[92:95], v[68:83]
	s_waitcnt lgkmcnt(0)
	v_mfma_f32_32x32x16_bf16 v[68:83], v[142:145], v[96:99], v[68:83]
	ds_read_b128 v[142:145], v2 offset:4096
	s_waitcnt lgkmcnt(0)
	v_mfma_f32_32x32x16_bf16 v[68:83], v[142:145], v[100:103], v[68:83]
	v_mfma_f32_32x32x16_bf16 v[52:67], v[154:157], v[100:103], v[52:67]
	s_cbranch_scc1 .LBB0_837
	s_nop 10
	v_cndmask_b32_e64 v142, v52, v121, s[2:3]
	v_cndmask_b32_e64 v68, v68, v121, s[4:5]
	v_cndmask_b32_e64 v52, v142, v52, s[6:7]
	v_cndmask_b32_e64 v53, v121, v53, s[6:7]
	v_cndmask_b32_e64 v69, v69, v121, s[8:9]
	v_cndmask_b32_e64 v54, v54, v121, s[10:11]
	v_cndmask_b32_e64 v70, v70, v121, s[12:13]
	v_cndmask_b32_e64 v55, v55, v121, s[14:15]
	v_cndmask_b32_e64 v71, v71, v121, s[16:17]
	v_cndmask_b32_e64 v56, v56, v121, s[18:19]
	v_cndmask_b32_e64 v72, v72, v121, s[20:21]
	v_cndmask_b32_e64 v57, v57, v121, s[22:23]
	v_cndmask_b32_e64 v73, v73, v121, s[24:25]
	v_cndmask_b32_e64 v58, v58, v121, s[26:27]
	v_cndmask_b32_e64 v74, v74, v121, s[28:29]
	v_cndmask_b32_e64 v59, v59, v121, s[30:31]
	v_cndmask_b32_e64 v75, v75, v121, s[34:35]
	v_cndmask_b32_e64 v60, v60, v121, s[36:37]
	v_cndmask_b32_e64 v76, v76, v121, s[38:39]
	v_cndmask_b32_e64 v61, v61, v121, s[40:41]
	v_cndmask_b32_e64 v77, v77, v121, s[42:43]
	v_cndmask_b32_e64 v62, v62, v121, s[44:45]
	v_cndmask_b32_e64 v78, v78, v121, s[46:47]
	v_cndmask_b32_e64 v63, v63, v121, s[48:49]
	v_cndmask_b32_e64 v79, v79, v121, s[50:51]
	v_cndmask_b32_e64 v64, v64, v121, s[52:53]
	v_cndmask_b32_e64 v80, v80, v121, s[54:55]
	v_cndmask_b32_e64 v65, v65, v121, s[56:57]
	v_cndmask_b32_e64 v81, v81, v121, s[58:59]
	v_cndmask_b32_e64 v66, v66, v121, s[60:61]
	v_cndmask_b32_e64 v82, v82, v121, s[62:63]
	v_cndmask_b32_e64 v67, v67, v121, s[64:65]
	v_cndmask_b32_e64 v83, v83, v121, s[66:67]
.LBB0_837:
	s_andn2_b64 vcc, exec, s[0:1]
	s_cbranch_vccnz .LBB0_843
	s_setprio 0
	s_nop 8
	v_max_f32_e32 v142, v52, v53
	v_max3_f32 v142, v142, v54, v55
	v_max3_f32 v142, v142, v56, v57
	v_max3_f32 v142, v142, v58, v59
	v_max3_f32 v142, v142, v60, v61
	v_max3_f32 v142, v142, v62, v63
	v_max3_f32 v142, v142, v64, v65
	v_max3_f32 v142, v142, v66, v67
	v_mov_b32_e32 v143, v142
	s_nop 1
	v_permlane32_swap_b32_e32 v142, v143
	v_max_f32_e32 v142, v142, v143
	s_cmp_eq_u32 s96, 0
	s_cselect_b64 s[0:1], -1, 0
	v_cmp_lt_f32_e32 vcc, s95, v142
	s_or_b64 vcc, s[0:1], vcc
	s_cbranch_vccz .LBB0_840
	v_max_f32_e32 v143, v142, v142
	v_max_f32_e32 v143, 0, v143
	v_cndmask_b32_e64 v142, v143, v142, s[0:1]
	v_exp_f32_e64 v143, -v142
	v_add_f32_e32 v137, v137, v142
	v_sub_f32_e32 v83, v83, v142
	v_sub_f32_e32 v82, v82, v142
	v_cndmask_b32_e64 v144, v143, 1.0, s[0:1]
	v_pk_add_f32 v[52:53], v[52:53], v[142:143] op_sel_hi:[1,0] neg_lo:[0,1] neg_hi:[0,1]
	v_pk_add_f32 v[54:55], v[54:55], v[142:143] op_sel_hi:[1,0] neg_lo:[0,1] neg_hi:[0,1]
	v_mul_f32_e32 v36, v36, v144
	v_pk_add_f32 v[56:57], v[56:57], v[142:143] op_sel_hi:[1,0] neg_lo:[0,1] neg_hi:[0,1]
	v_pk_add_f32 v[58:59], v[58:59], v[142:143] op_sel_hi:[1,0] neg_lo:[0,1] neg_hi:[0,1]
	v_pk_add_f32 v[60:61], v[60:61], v[142:143] op_sel_hi:[1,0] neg_lo:[0,1] neg_hi:[0,1]
	v_pk_add_f32 v[62:63], v[62:63], v[142:143] op_sel_hi:[1,0] neg_lo:[0,1] neg_hi:[0,1]
	v_pk_add_f32 v[64:65], v[64:65], v[142:143] op_sel_hi:[1,0] neg_lo:[0,1] neg_hi:[0,1]
	v_pk_add_f32 v[66:67], v[66:67], v[142:143] op_sel_hi:[1,0] neg_lo:[0,1] neg_hi:[0,1]
	v_sub_f32_e32 v81, v81, v142
	v_sub_f32_e32 v80, v80, v142
	v_sub_f32_e32 v79, v79, v142
	v_sub_f32_e32 v78, v78, v142
	v_sub_f32_e32 v77, v77, v142
	v_sub_f32_e32 v76, v76, v142
	v_sub_f32_e32 v75, v75, v142
	v_sub_f32_e32 v74, v74, v142
	v_sub_f32_e32 v73, v73, v142
	v_sub_f32_e32 v72, v72, v142
	v_sub_f32_e32 v71, v71, v142
	v_sub_f32_e32 v70, v70, v142
	v_sub_f32_e32 v69, v69, v142
	v_sub_f32_e32 v68, v68, v142
	v_pk_mul_f32 v[34:35], v[34:35], v[144:145] op_sel_hi:[1,0]
	v_pk_mul_f32 v[32:33], v[32:33], v[144:145] op_sel_hi:[1,0]
	v_pk_mul_f32 v[30:31], v[30:31], v[144:145] op_sel_hi:[1,0]
	v_pk_mul_f32 v[28:29], v[28:29], v[144:145] op_sel_hi:[1,0]
	v_pk_mul_f32 v[26:27], v[26:27], v[144:145] op_sel_hi:[1,0]
	v_pk_mul_f32 v[24:25], v[24:25], v[144:145] op_sel_hi:[1,0]
	v_pk_mul_f32 v[22:23], v[22:23], v[144:145] op_sel_hi:[1,0]
	v_pk_mul_f32 v[20:21], v[20:21], v[144:145] op_sel_hi:[1,0]
	v_pk_mul_f32 v[18:19], v[18:19], v[144:145] op_sel_hi:[1,0]
	v_pk_mul_f32 v[16:17], v[16:17], v[144:145] op_sel_hi:[1,0]
	v_pk_mul_f32 v[14:15], v[14:15], v[144:145] op_sel_hi:[1,0]
	v_pk_mul_f32 v[12:13], v[12:13], v[144:145] op_sel_hi:[1,0]
	v_pk_mul_f32 v[10:11], v[10:11], v[144:145] op_sel_hi:[1,0]
	v_pk_mul_f32 v[8:9], v[8:9], v[144:145] op_sel_hi:[1,0]
	v_pk_mul_f32 v[6:7], v[6:7], v[144:145] op_sel_hi:[1,0]
	v_pk_mul_f32 v[4:5], v[4:5], v[144:145] op_sel_hi:[1,0]

.LBB0_843:
	s_cmp_lt_u32 s77, s73
	s_cselect_b64 s[0:1], -1, 0
	s_cmp_ge_u32 s77, s73
	s_cbranch_scc1 .LBB0_846
	s_setprio 1
	s_nop 4
	v_mov_b32_e32 v52, s68
	ds_read_b32 v60, v52
	v_sub_f32_e32 v61, v1, v137
	ds_read_b128 v[76:79], v141 offset:33088
	ds_read_b128 v[52:55], v141 offset:33024
	ds_read_b128 v[56:59], v141 offset:33056
	s_waitcnt lgkmcnt(0)
	v_sub_f32_e32 v158, v61, v60
	ds_read_b128 v[60:63], v141 offset:33120
	ds_read_b128 v[146:149], v139 offset:8192
	v_sub_f32_e32 v55, v158, v55
	v_sub_f32_e32 v59, v158, v59
	v_sub_f32_e32 v58, v158, v58
	s_waitcnt lgkmcnt(0)
	v_sub_f32_e32 v67, v158, v63
	v_sub_f32_e32 v66, v158, v62
	v_sub_f32_e32 v65, v158, v61
	v_sub_f32_e32 v64, v158, v60
	v_sub_f32_e32 v63, v158, v79
	v_sub_f32_e32 v62, v158, v78
	v_sub_f32_e32 v61, v158, v77
	v_sub_f32_e32 v60, v158, v76
	ds_read_b128 v[76:79], v140 offset:8192
	v_sub_f32_e32 v57, v158, v57
	v_sub_f32_e32 v56, v158, v56
	v_sub_f32_e32 v54, v158, v54
	v_sub_f32_e32 v53, v158, v53
	v_sub_f32_e32 v52, v158, v52
	ds_read_b128 v[68:71], v141 offset:33152
	ds_read_b128 v[72:75], v141 offset:33184
	ds_read_b128 v[142:145], v141 offset:33216
	ds_read_b128 v[80:83], v141 offset:33248
	ds_read_b128 v[150:153], v138 offset:8192
	s_waitcnt lgkmcnt(0)
	v_mfma_f32_32x32x16_bf16 v[52:67], v[76:79], v[88:91], v[52:67]
	ds_read_b128 v[154:157], v2 offset:8192
	v_sub_f32_e32 v77, v158, v143
	v_sub_f32_e32 v76, v158, v142
	v_sub_f32_e32 v83, v158, v83
	v_sub_f32_e32 v82, v158, v82
	v_sub_f32_e32 v81, v158, v81
	v_sub_f32_e32 v80, v158, v80
	v_mfma_f32_32x32x16_bf16 v[52:67], v[146:149], v[92:95], v[52:67]
	ds_read_b128 v[140:143], v140 offset:12288
	v_sub_f32_e32 v79, v158, v145
	v_sub_f32_e32 v78, v158, v144
	v_sub_f32_e32 v75, v158, v75
	v_sub_f32_e32 v74, v158, v74
	v_sub_f32_e32 v73, v158, v73
	v_sub_f32_e32 v72, v158, v72
	v_mfma_f32_32x32x16_bf16 v[52:67], v[150:153], v[96:99], v[52:67]
	v_sub_f32_e32 v71, v158, v71
	v_sub_f32_e32 v70, v158, v70
	v_sub_f32_e32 v69, v158, v69
	v_sub_f32_e32 v68, v158, v68
	ds_read_b128 v[144:147], v139 offset:12288
	s_cmp_lg_u32 s93, s77
	s_waitcnt lgkmcnt(0)
	v_mfma_f32_32x32x16_bf16 v[68:83], v[140:143], v[88:91], v[68:83]
	ds_read_b128 v[138:141], v138 offset:12288
	v_mfma_f32_32x32x16_bf16 v[68:83], v[144:147], v[92:95], v[68:83]
	s_waitcnt lgkmcnt(0)
	v_mfma_f32_32x32x16_bf16 v[68:83], v[138:141], v[96:99], v[68:83]
	ds_read_b128 v[138:141], v2 offset:12288
	s_waitcnt lgkmcnt(0)
	v_mfma_f32_32x32x16_bf16 v[68:83], v[138:141], v[100:103], v[68:83]
	v_mfma_f32_32x32x16_bf16 v[52:67], v[154:157], v[100:103], v[52:67]
	s_cbranch_scc1 .LBB0_846
	s_nop 10
	v_cndmask_b32_e64 v2, v52, v121, s[2:3]
	v_cndmask_b32_e64 v68, v68, v121, s[4:5]
	v_cndmask_b32_e64 v52, v2, v52, s[6:7]
	v_cndmask_b32_e64 v53, v121, v53, s[6:7]
	v_cndmask_b32_e64 v69, v69, v121, s[8:9]
	v_cndmask_b32_e64 v54, v54, v121, s[10:11]
	v_cndmask_b32_e64 v70, v70, v121, s[12:13]
	v_cndmask_b32_e64 v55, v55, v121, s[14:15]
	v_cndmask_b32_e64 v71, v71, v121, s[16:17]
	v_cndmask_b32_e64 v56, v56, v121, s[18:19]
	v_cndmask_b32_e64 v72, v72, v121, s[20:21]
	v_cndmask_b32_e64 v57, v57, v121, s[22:23]
	v_cndmask_b32_e64 v73, v73, v121, s[24:25]
	v_cndmask_b32_e64 v58, v58, v121, s[26:27]
	v_cndmask_b32_e64 v74, v74, v121, s[28:29]
	v_cndmask_b32_e64 v59, v59, v121, s[30:31]
	v_cndmask_b32_e64 v75, v75, v121, s[34:35]
	v_cndmask_b32_e64 v60, v60, v121, s[36:37]
	v_cndmask_b32_e64 v76, v76, v121, s[38:39]
	v_cndmask_b32_e64 v61, v61, v121, s[40:41]
	v_cndmask_b32_e64 v77, v77, v121, s[42:43]
	v_cndmask_b32_e64 v62, v62, v121, s[44:45]
	v_cndmask_b32_e64 v78, v78, v121, s[46:47]
	v_cndmask_b32_e64 v63, v63, v121, s[48:49]
	v_cndmask_b32_e64 v79, v79, v121, s[50:51]
	v_cndmask_b32_e64 v64, v64, v121, s[52:53]
	v_cndmask_b32_e64 v80, v80, v121, s[54:55]
	v_cndmask_b32_e64 v65, v65, v121, s[56:57]
	v_cndmask_b32_e64 v81, v81, v121, s[58:59]
	v_cndmask_b32_e64 v66, v66, v121, s[60:61]
	v_cndmask_b32_e64 v82, v82, v121, s[62:63]
	v_cndmask_b32_e64 v67, v67, v121, s[64:65]
	v_cndmask_b32_e64 v83, v83, v121, s[66:67]
.LBB0_846:
	s_andn2_b64 vcc, exec, s[0:1]
	s_cbranch_vccnz .LBB0_852
	s_setprio 0
	s_nop 8
	v_max_f32_e32 v2, v52, v53
	v_max3_f32 v2, v2, v54, v55
	v_max3_f32 v2, v2, v56, v57
	v_max3_f32 v2, v2, v58, v59
	v_max3_f32 v2, v2, v60, v61
	v_max3_f32 v2, v2, v62, v63
	v_max3_f32 v2, v2, v64, v65
	v_max3_f32 v2, v2, v66, v67
	v_mov_b32_e32 v138, v2
	s_nop 1
	v_permlane32_swap_b32_e32 v2, v138
	v_max_f32_e32 v2, v2, v138
	v_cmp_lt_f32_e32 vcc, s95, v2
	s_cbranch_vccz .LBB0_849
	v_max_f32_e32 v2, v2, v2
	v_max_f32_e32 v2, 0, v2
	v_exp_f32_e64 v138, -v2
	v_add_f32_e32 v137, v137, v2
	v_pk_add_f32 v[52:53], v[52:53], v[2:3] op_sel_hi:[1,0] neg_lo:[0,1] neg_hi:[0,1]
	v_pk_add_f32 v[54:55], v[54:55], v[2:3] op_sel_hi:[1,0] neg_lo:[0,1] neg_hi:[0,1]
	v_mul_f32_e32 v36, v36, v138
	v_pk_add_f32 v[56:57], v[56:57], v[2:3] op_sel_hi:[1,0] neg_lo:[0,1] neg_hi:[0,1]
	v_pk_add_f32 v[58:59], v[58:59], v[2:3] op_sel_hi:[1,0] neg_lo:[0,1] neg_hi:[0,1]
	v_pk_add_f32 v[60:61], v[60:61], v[2:3] op_sel_hi:[1,0] neg_lo:[0,1] neg_hi:[0,1]
	v_pk_add_f32 v[62:63], v[62:63], v[2:3] op_sel_hi:[1,0] neg_lo:[0,1] neg_hi:[0,1]
	v_pk_add_f32 v[64:65], v[64:65], v[2:3] op_sel_hi:[1,0] neg_lo:[0,1] neg_hi:[0,1]
	v_pk_add_f32 v[66:67], v[66:67], v[2:3] op_sel_hi:[1,0] neg_lo:[0,1] neg_hi:[0,1]
	v_sub_f32_e32 v83, v83, v2
	v_sub_f32_e32 v82, v82, v2
	v_sub_f32_e32 v81, v81, v2
	v_sub_f32_e32 v80, v80, v2
	v_sub_f32_e32 v79, v79, v2
	v_sub_f32_e32 v78, v78, v2
	v_sub_f32_e32 v77, v77, v2
	v_sub_f32_e32 v76, v76, v2
	v_sub_f32_e32 v75, v75, v2
	v_sub_f32_e32 v74, v74, v2
	v_sub_f32_e32 v73, v73, v2
	v_sub_f32_e32 v72, v72, v2
	v_sub_f32_e32 v71, v71, v2
	v_sub_f32_e32 v70, v70, v2
	v_sub_f32_e32 v69, v69, v2
	v_sub_f32_e32 v68, v68, v2
	v_pk_mul_f32 v[34:35], v[34:35], v[138:139] op_sel_hi:[1,0]
	v_pk_mul_f32 v[32:33], v[32:33], v[138:139] op_sel_hi:[1,0]
	v_pk_mul_f32 v[30:31], v[30:31], v[138:139] op_sel_hi:[1,0]
	v_pk_mul_f32 v[28:29], v[28:29], v[138:139] op_sel_hi:[1,0]
	v_pk_mul_f32 v[26:27], v[26:27], v[138:139] op_sel_hi:[1,0]
	v_pk_mul_f32 v[24:25], v[24:25], v[138:139] op_sel_hi:[1,0]
	v_pk_mul_f32 v[22:23], v[22:23], v[138:139] op_sel_hi:[1,0]
	v_pk_mul_f32 v[20:21], v[20:21], v[138:139] op_sel_hi:[1,0]
	v_pk_mul_f32 v[18:19], v[18:19], v[138:139] op_sel_hi:[1,0]
	v_pk_mul_f32 v[16:17], v[16:17], v[138:139] op_sel_hi:[1,0]
	v_pk_mul_f32 v[14:15], v[14:15], v[138:139] op_sel_hi:[1,0]
	v_pk_mul_f32 v[12:13], v[12:13], v[138:139] op_sel_hi:[1,0]
	v_pk_mul_f32 v[10:11], v[10:11], v[138:139] op_sel_hi:[1,0]
	v_pk_mul_f32 v[8:9], v[8:9], v[138:139] op_sel_hi:[1,0]
	v_pk_mul_f32 v[6:7], v[6:7], v[138:139] op_sel_hi:[1,0]
	v_pk_mul_f32 v[4:5], v[4:5], v[138:139] op_sel_hi:[1,0]

.LBB0_946:
	s_add_i32 s93, s0, 0
	s_lshl_b32 s0, s1, 1
	s_and_b32 s0, s0, -4
	s_add_i32 s94, s0, 0
	s_add_i32 s94, s94, 0x1b000
	s_cmp_le_u32 s77, s33
	v_lshl_add_u32 v121, v132, 2, s93
	s_cselect_b64 s[0:1], -1, 0
	s_cmp_gt_u32 s77, s33
	v_add_u32_e32 v119, s93, v125
	v_add_u32_e32 v117, s93, v126
	v_add_u32_e32 v115, s93, v127
	v_add_u32_e32 v0, s93, v128
	s_cbranch_scc1 .LBB0_949
	s_setprio 1
	v_mov_b32_e32 v50, s94
	ds_read_b32 v58, v50
	v_sub_f32_e32 v59, v82, v113
	ds_read_b128 v[74:77], v121 offset:32832
	ds_read_b128 v[50:53], v121 offset:32768
	ds_read_b128 v[54:57], v121 offset:32800
	s_waitcnt lgkmcnt(0)
	v_sub_f32_e32 v122, v59, v58
	ds_read_b128 v[58:61], v121 offset:32864
	ds_read_b128 v[142:145], v117
	v_sub_f32_e32 v53, v122, v53
	v_sub_f32_e32 v57, v122, v57
	v_sub_f32_e32 v56, v122, v56
	s_waitcnt lgkmcnt(0)
	v_sub_f32_e32 v65, v122, v61
	v_sub_f32_e32 v64, v122, v60
	v_sub_f32_e32 v63, v122, v59
	v_sub_f32_e32 v62, v122, v58
	v_sub_f32_e32 v61, v122, v77
	v_sub_f32_e32 v60, v122, v76
	v_sub_f32_e32 v59, v122, v75
	v_sub_f32_e32 v58, v122, v74
	ds_read_b128 v[74:77], v119
	v_sub_f32_e32 v55, v122, v55
	v_sub_f32_e32 v54, v122, v54
	v_sub_f32_e32 v52, v122, v52
	v_sub_f32_e32 v51, v122, v51
	v_sub_f32_e32 v50, v122, v50
	ds_read_b128 v[66:69], v121 offset:32896
	ds_read_b128 v[70:73], v121 offset:32928
	ds_read_b128 v[138:141], v121 offset:32960
	ds_read_b128 v[78:81], v121 offset:32992
	ds_read_b128 v[146:149], v115
	s_waitcnt lgkmcnt(0)
	v_mfma_f32_32x32x16_bf16 v[50:65], v[74:77], v[88:91], v[50:65]
	ds_read_b128 v[150:153], v0
	v_sub_f32_e32 v77, v122, v141
	v_sub_f32_e32 v76, v122, v140
	v_sub_f32_e32 v75, v122, v139
	v_sub_f32_e32 v74, v122, v138
	v_sub_f32_e32 v81, v122, v81
	v_sub_f32_e32 v80, v122, v80
	v_mfma_f32_32x32x16_bf16 v[50:65], v[142:145], v[92:95], v[50:65]
	ds_read_b128 v[138:141], v119 offset:4096
	v_sub_f32_e32 v79, v122, v79
	v_sub_f32_e32 v78, v122, v78
	v_sub_f32_e32 v73, v122, v73
	v_sub_f32_e32 v72, v122, v72
	v_sub_f32_e32 v71, v122, v71
	v_sub_f32_e32 v70, v122, v70
	v_mfma_f32_32x32x16_bf16 v[50:65], v[146:149], v[96:99], v[50:65]
	v_sub_f32_e32 v69, v122, v69
	v_sub_f32_e32 v68, v122, v68
	v_sub_f32_e32 v67, v122, v67
	v_sub_f32_e32 v66, v122, v66
	ds_read_b128 v[142:145], v117 offset:4096
	s_cmp_lg_u32 s33, s77
	s_waitcnt lgkmcnt(0)
	v_mfma_f32_32x32x16_bf16 v[66:81], v[138:141], v[88:91], v[66:81]
	ds_read_b128 v[138:141], v115 offset:4096
	v_mfma_f32_32x32x16_bf16 v[66:81], v[142:145], v[92:95], v[66:81]
	s_waitcnt lgkmcnt(0)
	v_mfma_f32_32x32x16_bf16 v[66:81], v[138:141], v[96:99], v[66:81]
	ds_read_b128 v[138:141], v0 offset:4096
	s_waitcnt lgkmcnt(0)
	v_mfma_f32_32x32x16_bf16 v[66:81], v[138:141], v[100:103], v[66:81]
	v_mfma_f32_32x32x16_bf16 v[50:65], v[150:153], v[100:103], v[50:65]
	s_cbranch_scc1 .LBB0_949
	s_nop 10
	v_cndmask_b32_e64 v122, v50, v109, s[2:3]
	v_cndmask_b32_e64 v66, v66, v109, s[4:5]
	v_cndmask_b32_e64 v50, v122, v50, s[6:7]
	v_cndmask_b32_e64 v51, v109, v51, s[6:7]
	v_cndmask_b32_e64 v67, v67, v109, s[8:9]
	v_cndmask_b32_e64 v52, v52, v109, s[10:11]
	v_cndmask_b32_e64 v68, v68, v109, s[12:13]
	v_cndmask_b32_e64 v53, v53, v109, s[14:15]
	v_cndmask_b32_e64 v69, v69, v109, s[16:17]
	v_cndmask_b32_e64 v54, v54, v109, s[18:19]
	v_cndmask_b32_e64 v70, v70, v109, s[20:21]
	v_cndmask_b32_e64 v55, v55, v109, s[22:23]
	v_cndmask_b32_e64 v71, v71, v109, s[24:25]
	v_cndmask_b32_e64 v56, v56, v109, s[26:27]
	v_cndmask_b32_e64 v72, v72, v109, s[28:29]
	v_cndmask_b32_e64 v57, v57, v109, s[30:31]
	v_cndmask_b32_e64 v73, v73, v109, s[34:35]
	v_cndmask_b32_e64 v58, v58, v109, s[36:37]
	v_cndmask_b32_e64 v74, v74, v109, s[38:39]
	v_cndmask_b32_e64 v59, v59, v109, s[40:41]
	v_cndmask_b32_e64 v75, v75, v109, s[42:43]
	v_cndmask_b32_e64 v60, v60, v109, s[44:45]
	v_cndmask_b32_e64 v76, v76, v109, s[46:47]
	v_cndmask_b32_e64 v61, v61, v109, s[48:49]
	v_cndmask_b32_e64 v77, v77, v109, s[50:51]
	v_cndmask_b32_e64 v62, v62, v109, s[52:53]
	v_cndmask_b32_e64 v78, v78, v109, s[54:55]
	v_cndmask_b32_e64 v63, v63, v109, s[56:57]
	v_cndmask_b32_e64 v79, v79, v109, s[58:59]
	v_cndmask_b32_e64 v64, v64, v109, s[60:61]
	v_cndmask_b32_e64 v80, v80, v109, s[62:63]
	v_cndmask_b32_e64 v65, v65, v109, s[64:65]
	v_cndmask_b32_e64 v81, v81, v109, s[66:67]
.LBB0_949:
	s_andn2_b64 vcc, exec, s[0:1]
	s_cbranch_vccnz .LBB0_955
	s_setprio 0
	s_nop 8
	v_max_f32_e32 v122, v50, v51
	v_max3_f32 v122, v122, v52, v53
	v_max3_f32 v122, v122, v54, v55
	v_max3_f32 v122, v122, v56, v57
	v_max3_f32 v122, v122, v58, v59
	v_max3_f32 v122, v122, v60, v61
	v_max3_f32 v122, v122, v62, v63
	v_max3_f32 v122, v122, v64, v65
	v_mov_b32_e32 v123, v122
	s_nop 1
	v_permlane32_swap_b32_e32 v122, v123
	v_max_f32_e32 v122, v122, v123
	s_cmp_eq_u32 s90, 0
	s_cselect_b64 s[0:1], -1, 0
	v_cmp_lt_f32_e32 vcc, s92, v122
	s_or_b64 vcc, s[0:1], vcc
	s_cbranch_vccz .LBB0_952
	v_max_f32_e32 v123, v122, v122
	v_max_f32_e32 v123, 0, v123
	v_cndmask_b32_e64 v122, v123, v122, s[0:1]
	v_exp_f32_e64 v123, -v122
	v_add_f32_e32 v113, v113, v122
	v_sub_f32_e32 v81, v81, v122
	v_sub_f32_e32 v80, v80, v122
	v_cndmask_b32_e64 v134, v123, 1.0, s[0:1]
	v_pk_add_f32 v[50:51], v[50:51], v[122:123] op_sel_hi:[1,0] neg_lo:[0,1] neg_hi:[0,1]
	v_pk_add_f32 v[52:53], v[52:53], v[122:123] op_sel_hi:[1,0] neg_lo:[0,1] neg_hi:[0,1]
	v_mul_f32_e32 v34, v34, v134
	v_pk_add_f32 v[54:55], v[54:55], v[122:123] op_sel_hi:[1,0] neg_lo:[0,1] neg_hi:[0,1]
	v_pk_add_f32 v[56:57], v[56:57], v[122:123] op_sel_hi:[1,0] neg_lo:[0,1] neg_hi:[0,1]
	v_pk_add_f32 v[58:59], v[58:59], v[122:123] op_sel_hi:[1,0] neg_lo:[0,1] neg_hi:[0,1]
	v_pk_add_f32 v[60:61], v[60:61], v[122:123] op_sel_hi:[1,0] neg_lo:[0,1] neg_hi:[0,1]
	v_pk_add_f32 v[62:63], v[62:63], v[122:123] op_sel_hi:[1,0] neg_lo:[0,1] neg_hi:[0,1]
	v_pk_add_f32 v[64:65], v[64:65], v[122:123] op_sel_hi:[1,0] neg_lo:[0,1] neg_hi:[0,1]
	v_sub_f32_e32 v79, v79, v122
	v_sub_f32_e32 v78, v78, v122
	v_sub_f32_e32 v77, v77, v122
	v_sub_f32_e32 v76, v76, v122
	v_sub_f32_e32 v75, v75, v122
	v_sub_f32_e32 v74, v74, v122
	v_sub_f32_e32 v73, v73, v122
	v_sub_f32_e32 v72, v72, v122
	v_sub_f32_e32 v71, v71, v122
	v_sub_f32_e32 v70, v70, v122
	v_sub_f32_e32 v69, v69, v122
	v_sub_f32_e32 v68, v68, v122
	v_sub_f32_e32 v67, v67, v122
	v_sub_f32_e32 v66, v66, v122
	v_pk_mul_f32 v[32:33], v[32:33], v[134:135] op_sel_hi:[1,0]
	v_pk_mul_f32 v[30:31], v[30:31], v[134:135] op_sel_hi:[1,0]
	v_pk_mul_f32 v[28:29], v[28:29], v[134:135] op_sel_hi:[1,0]
	v_pk_mul_f32 v[26:27], v[26:27], v[134:135] op_sel_hi:[1,0]
	v_pk_mul_f32 v[24:25], v[24:25], v[134:135] op_sel_hi:[1,0]
	v_pk_mul_f32 v[22:23], v[22:23], v[134:135] op_sel_hi:[1,0]
	v_pk_mul_f32 v[20:21], v[20:21], v[134:135] op_sel_hi:[1,0]
	v_pk_mul_f32 v[18:19], v[18:19], v[134:135] op_sel_hi:[1,0]
	v_pk_mul_f32 v[16:17], v[16:17], v[134:135] op_sel_hi:[1,0]
	v_pk_mul_f32 v[14:15], v[14:15], v[134:135] op_sel_hi:[1,0]
	v_pk_mul_f32 v[12:13], v[12:13], v[134:135] op_sel_hi:[1,0]
	v_pk_mul_f32 v[10:11], v[10:11], v[134:135] op_sel_hi:[1,0]
	v_pk_mul_f32 v[8:9], v[8:9], v[134:135] op_sel_hi:[1,0]
	v_pk_mul_f32 v[6:7], v[6:7], v[134:135] op_sel_hi:[1,0]
	v_pk_mul_f32 v[4:5], v[4:5], v[134:135] op_sel_hi:[1,0]
	v_pk_mul_f32 v[2:3], v[2:3], v[134:135] op_sel_hi:[1,0]

.LBB0_955:
	s_cmp_lt_u32 s77, s33
	s_cselect_b64 s[0:1], -1, 0
	s_cmp_ge_u32 s77, s33
	s_cbranch_scc1 .LBB0_958
	s_setprio 1
	s_nop 4
	v_mov_b32_e32 v50, s94
	ds_read_b32 v58, v50
	v_sub_f32_e32 v59, v82, v113
	ds_read_b128 v[74:77], v121 offset:33088
	ds_read_b128 v[50:53], v121 offset:33024
	ds_read_b128 v[54:57], v121 offset:33056
	s_waitcnt lgkmcnt(0)
	v_sub_f32_e32 v122, v59, v58
	ds_read_b128 v[58:61], v121 offset:33120
	ds_read_b128 v[142:145], v117 offset:8192
	v_sub_f32_e32 v53, v122, v53
	v_sub_f32_e32 v57, v122, v57
	v_sub_f32_e32 v56, v122, v56
	s_waitcnt lgkmcnt(0)
	v_sub_f32_e32 v65, v122, v61
	v_sub_f32_e32 v64, v122, v60
	v_sub_f32_e32 v63, v122, v59
	v_sub_f32_e32 v62, v122, v58
	v_sub_f32_e32 v61, v122, v77
	v_sub_f32_e32 v60, v122, v76
	v_sub_f32_e32 v59, v122, v75
	v_sub_f32_e32 v58, v122, v74
	ds_read_b128 v[74:77], v119 offset:8192
	v_sub_f32_e32 v55, v122, v55
	v_sub_f32_e32 v54, v122, v54
	v_sub_f32_e32 v52, v122, v52
	v_sub_f32_e32 v51, v122, v51
	v_sub_f32_e32 v50, v122, v50
	ds_read_b128 v[66:69], v121 offset:33152
	ds_read_b128 v[70:73], v121 offset:33184
	ds_read_b128 v[138:141], v121 offset:33216
	ds_read_b128 v[78:81], v121 offset:33248
	ds_read_b128 v[146:149], v115 offset:8192
	s_waitcnt lgkmcnt(0)
	v_mfma_f32_32x32x16_bf16 v[50:65], v[74:77], v[88:91], v[50:65]
	ds_read_b128 v[150:153], v0 offset:8192
	v_sub_f32_e32 v77, v122, v141
	v_sub_f32_e32 v76, v122, v140
	v_sub_f32_e32 v75, v122, v139
	v_sub_f32_e32 v74, v122, v138
	v_sub_f32_e32 v81, v122, v81
	v_sub_f32_e32 v80, v122, v80
	v_mfma_f32_32x32x16_bf16 v[50:65], v[142:145], v[92:95], v[50:65]
	ds_read_b128 v[138:141], v119 offset:12288
	v_sub_f32_e32 v79, v122, v79
	v_sub_f32_e32 v78, v122, v78
	v_sub_f32_e32 v73, v122, v73
	v_sub_f32_e32 v72, v122, v72
	v_sub_f32_e32 v71, v122, v71
	v_sub_f32_e32 v70, v122, v70
	v_mfma_f32_32x32x16_bf16 v[50:65], v[146:149], v[96:99], v[50:65]
	v_sub_f32_e32 v69, v122, v69
	v_sub_f32_e32 v68, v122, v68
	v_sub_f32_e32 v67, v122, v67
	v_sub_f32_e32 v66, v122, v66
	ds_read_b128 v[142:145], v117 offset:12288
	s_cmp_lg_u32 s68, s77
	s_waitcnt lgkmcnt(0)
	v_mfma_f32_32x32x16_bf16 v[66:81], v[138:141], v[88:91], v[66:81]
	ds_read_b128 v[138:141], v115 offset:12288
	v_mfma_f32_32x32x16_bf16 v[66:81], v[142:145], v[92:95], v[66:81]
	s_waitcnt lgkmcnt(0)
	v_mfma_f32_32x32x16_bf16 v[66:81], v[138:141], v[96:99], v[66:81]
	ds_read_b128 v[138:141], v0 offset:12288
	s_waitcnt lgkmcnt(0)
	v_mfma_f32_32x32x16_bf16 v[66:81], v[138:141], v[100:103], v[66:81]
	v_mfma_f32_32x32x16_bf16 v[50:65], v[150:153], v[100:103], v[50:65]
	s_cbranch_scc1 .LBB0_958
	s_nop 10
	v_cndmask_b32_e64 v0, v50, v109, s[2:3]
	v_cndmask_b32_e64 v66, v66, v109, s[4:5]
	v_cndmask_b32_e64 v50, v0, v50, s[6:7]
	v_cndmask_b32_e64 v51, v109, v51, s[6:7]
	v_cndmask_b32_e64 v67, v67, v109, s[8:9]
	v_cndmask_b32_e64 v52, v52, v109, s[10:11]
	v_cndmask_b32_e64 v68, v68, v109, s[12:13]
	v_cndmask_b32_e64 v53, v53, v109, s[14:15]
	v_cndmask_b32_e64 v69, v69, v109, s[16:17]
	v_cndmask_b32_e64 v54, v54, v109, s[18:19]
	v_cndmask_b32_e64 v70, v70, v109, s[20:21]
	v_cndmask_b32_e64 v55, v55, v109, s[22:23]
	v_cndmask_b32_e64 v71, v71, v109, s[24:25]
	v_cndmask_b32_e64 v56, v56, v109, s[26:27]
	v_cndmask_b32_e64 v72, v72, v109, s[28:29]
	v_cndmask_b32_e64 v57, v57, v109, s[30:31]
	v_cndmask_b32_e64 v73, v73, v109, s[34:35]
	v_cndmask_b32_e64 v58, v58, v109, s[36:37]
	v_cndmask_b32_e64 v74, v74, v109, s[38:39]
	v_cndmask_b32_e64 v59, v59, v109, s[40:41]
	v_cndmask_b32_e64 v75, v75, v109, s[42:43]
	v_cndmask_b32_e64 v60, v60, v109, s[44:45]
	v_cndmask_b32_e64 v76, v76, v109, s[46:47]
	v_cndmask_b32_e64 v61, v61, v109, s[48:49]
	v_cndmask_b32_e64 v77, v77, v109, s[50:51]
	v_cndmask_b32_e64 v62, v62, v109, s[52:53]
	v_cndmask_b32_e64 v78, v78, v109, s[54:55]
	v_cndmask_b32_e64 v63, v63, v109, s[56:57]
	v_cndmask_b32_e64 v79, v79, v109, s[58:59]
	v_cndmask_b32_e64 v64, v64, v109, s[60:61]
	v_cndmask_b32_e64 v80, v80, v109, s[62:63]
	v_cndmask_b32_e64 v65, v65, v109, s[64:65]
	v_cndmask_b32_e64 v81, v81, v109, s[66:67]
.LBB0_958:
	s_andn2_b64 vcc, exec, s[0:1]
	s_cbranch_vccnz .LBB0_964
	s_setprio 0
	s_nop 8
	v_max_f32_e32 v0, v50, v51
	v_max3_f32 v0, v0, v52, v53
	v_max3_f32 v0, v0, v54, v55
	v_max3_f32 v0, v0, v56, v57
	v_max3_f32 v0, v0, v58, v59
	v_max3_f32 v0, v0, v60, v61
	v_max3_f32 v0, v0, v62, v63
	v_max3_f32 v0, v0, v64, v65
	v_mov_b32_e32 v115, v0
	s_nop 1
	v_permlane32_swap_b32_e32 v0, v115
	v_max_f32_e32 v0, v0, v115
	v_cmp_lt_f32_e32 vcc, s92, v0
	s_cbranch_vccz .LBB0_961
	v_max_f32_e32 v0, v0, v0
	v_max_f32_e32 v0, 0, v0
	v_exp_f32_e64 v122, -v0
	v_add_f32_e32 v113, v113, v0
	v_pk_add_f32 v[50:51], v[50:51], v[0:1] op_sel_hi:[1,0] neg_lo:[0,1] neg_hi:[0,1]
	v_pk_add_f32 v[52:53], v[52:53], v[0:1] op_sel_hi:[1,0] neg_lo:[0,1] neg_hi:[0,1]
	v_mul_f32_e32 v34, v34, v122
	v_pk_add_f32 v[54:55], v[54:55], v[0:1] op_sel_hi:[1,0] neg_lo:[0,1] neg_hi:[0,1]
	v_pk_add_f32 v[56:57], v[56:57], v[0:1] op_sel_hi:[1,0] neg_lo:[0,1] neg_hi:[0,1]
	v_pk_add_f32 v[58:59], v[58:59], v[0:1] op_sel_hi:[1,0] neg_lo:[0,1] neg_hi:[0,1]
	v_pk_add_f32 v[60:61], v[60:61], v[0:1] op_sel_hi:[1,0] neg_lo:[0,1] neg_hi:[0,1]
	v_pk_add_f32 v[62:63], v[62:63], v[0:1] op_sel_hi:[1,0] neg_lo:[0,1] neg_hi:[0,1]
	v_pk_add_f32 v[64:65], v[64:65], v[0:1] op_sel_hi:[1,0] neg_lo:[0,1] neg_hi:[0,1]
	v_sub_f32_e32 v81, v81, v0
	v_sub_f32_e32 v80, v80, v0
	v_sub_f32_e32 v79, v79, v0
	v_sub_f32_e32 v78, v78, v0
	v_sub_f32_e32 v77, v77, v0
	v_sub_f32_e32 v76, v76, v0
	v_sub_f32_e32 v75, v75, v0
	v_sub_f32_e32 v74, v74, v0
	v_sub_f32_e32 v73, v73, v0
	v_sub_f32_e32 v72, v72, v0
	v_sub_f32_e32 v71, v71, v0
	v_sub_f32_e32 v70, v70, v0
	v_sub_f32_e32 v69, v69, v0
	v_sub_f32_e32 v68, v68, v0
	v_sub_f32_e32 v67, v67, v0
	v_sub_f32_e32 v66, v66, v0
	v_pk_mul_f32 v[32:33], v[32:33], v[122:123] op_sel_hi:[1,0]
	v_pk_mul_f32 v[30:31], v[30:31], v[122:123] op_sel_hi:[1,0]
	v_pk_mul_f32 v[28:29], v[28:29], v[122:123] op_sel_hi:[1,0]
	v_pk_mul_f32 v[26:27], v[26:27], v[122:123] op_sel_hi:[1,0]
	v_pk_mul_f32 v[24:25], v[24:25], v[122:123] op_sel_hi:[1,0]
	v_pk_mul_f32 v[22:23], v[22:23], v[122:123] op_sel_hi:[1,0]
	v_pk_mul_f32 v[20:21], v[20:21], v[122:123] op_sel_hi:[1,0]
	v_pk_mul_f32 v[18:19], v[18:19], v[122:123] op_sel_hi:[1,0]
	v_pk_mul_f32 v[16:17], v[16:17], v[122:123] op_sel_hi:[1,0]
	v_pk_mul_f32 v[14:15], v[14:15], v[122:123] op_sel_hi:[1,0]
	v_pk_mul_f32 v[12:13], v[12:13], v[122:123] op_sel_hi:[1,0]
	v_pk_mul_f32 v[10:11], v[10:11], v[122:123] op_sel_hi:[1,0]
	v_pk_mul_f32 v[8:9], v[8:9], v[122:123] op_sel_hi:[1,0]
	v_pk_mul_f32 v[6:7], v[6:7], v[122:123] op_sel_hi:[1,0]
	v_pk_mul_f32 v[4:5], v[4:5], v[122:123] op_sel_hi:[1,0]
	v_pk_mul_f32 v[2:3], v[2:3], v[122:123] op_sel_hi:[1,0]
